# FFN gate/up K blocks: same fragment prefetch inside the unrolled slices
# speedup vs baseline: 1.0527x; 1.0037x over previous
; template <int BM, class Epi>
; DI void gemm_tile(const bf16_t* __restrict__ A, int lda, const bf16_t* __restrict__ B, int ldb, int K, int row0, int col0, const Epi& epi, char* smem) {
;     constexpr int MI = BM / 64, NA_ = BM / 64;
;     const int tid = ltid(), lane = tid & 63, wave = tid >> 6, wm = wave >> 2, wn = wave & 3;
;     const int l31 = lane & 31, hh = lane >> 5, q = (lane & 15) >> 2, p = lane & 3, nblk = (lane >> 4) & 1;
;     f32x16 acc[MI][2];
; #pragma unroll
;     for (int i = 0; i < MI; ++i)
; #pragma unroll
;         for (int j = 0; j < 2; ++j)
; #pragma unroll
;             for (int r = 0; r < 16; ++r) acc[i][j][r] = 0.f;
;     u32x4 ra[NA_], rb[4];
;     const bf16_t* ag = A + (size_t)(row0 + (tid >> 3)) * lda + (tid & 7) * 8;
;     const bf16_t* bg = B + (size_t)(tid >> 5) * ldb + col0 + (tid & 31) * 8;
;     const int aw = (tid >> 3) * GA_S + (tid & 7) * 16, bw = BM * GA_S + (tid >> 5) * GB_S + (tid & 31) * 16;
;     const int nk = K >> 6;
;     const int xoff = (wm * (BM / 2) + l31) * GA_S + hh * 16;
;     const int woff = BM * GA_S + (hh * 8 + q) * GB_S + (wn * 64 + nblk * 16 + 4 * p) * 2;
; #pragma unroll
;     for (int i = 0; i < NA_; ++i) ra[i] = *(const u32x4*)(ag + (size_t)(64 * i) * lda);
; #pragma unroll
;     for (int i = 0; i < 4; ++i) rb[i] = *(const u32x4*)(bg + (size_t)(16 * i) * ldb);
;     __syncthreads();
; #pragma unroll
;     for (int i = 0; i < NA_; ++i) *(u32x4*)(smem + aw + 64 * i * GA_S) = ra[i];
; #pragma unroll
;     for (int i = 0; i < 4; ++i) *(u32x4*)(smem + bw + 16 * i * GB_S) = rb[i];
;     if (nk > 1) {
; #pragma unroll
;         for (int i = 0; i < NA_; ++i) ra[i] = *(const u32x4*)(ag + 64 + (size_t)(64 * i) * lda);
; #pragma unroll
;         for (int i = 0; i < 4; ++i) rb[i] = *(const u32x4*)(bg + (size_t)(64 + 16 * i) * ldb);
;     }
;     __syncthreads();
; template <class Epi>
; DI void gemm_phase(const bf16_t* A, int lda, const bf16_t* B, int ldb, int N, int K, const Epi& epi, char* smem, bool do_ctx = true) {
;     ...
;         const int xcd = bid & 7, loc = bid >> 3, per = G >> 3, mine = (RL / 256 / 8) * nt;
;         for (int i = loc; i < mine; i += per) {
;             const int cg = i >> 7, rem = i & 127, cw = min(8, nt - cg * 8);
;             int pg, w;
;             if (cw == 8) { pg = rem >> 5; w = rem & 31; } else { const int rr = i - cg * 128; pg = rr / (4 * cw); w = rr - pg * 4 * cw; }
.LBB0_1505:
	s_lshr_b32 s0, s11, 2
	s_add_i32 s1, s0, s6
	s_lshl_b32 s6, s11, 3
	s_lshl_b32 s0, s7, 5
	s_and_b32 s6, s6, 24
	s_or_b32 s0, s0, s6
	s_or_b32 s0, s0, s9
	v_mov_b32_e32 v177, v194
	s_lshl_b32 s0, s0, 8
	v_readlane_b32 s12, v253, 5
	v_ashrrev_i32_e32 v42, 3, v177
	v_add_u32_e32 v0, s0, v42
	v_ashrrev_i32_e32 v1, 31, v0
	v_lshlrev_b64 v[0:1], 11, v[0:1]
	v_readlane_b32 s13, v253, 6
	v_lshlrev_b32_e32 v2, 4, v177
	v_and_b32_e32 v172, 0x70, v2
	v_lshl_add_u64 v[0:1], s[12:13], 0, v[0:1]
	v_lshl_add_u64 v[136:137], v[0:1], 0, v[172:173]
	v_add_co_u32_e32 v138, vcc, s17, v136
	s_lshl_b32 s6, s1, 8
	s_nop 0
	v_addc_co_u32_e32 v139, vcc, 0, v137, vcc
	s_mov_b32 s1, 0x40000
	v_ashrrev_i32_e32 v43, 5, v177
	v_add_co_u32_e32 v140, vcc, s1, v136
	v_and_b32_e32 v178, 31, v177
	v_mad_i64_i32 v[0:1], s[12:13], v43, s33, v[174:175]
	s_ashr_i32 s7, s6, 31
	v_addc_co_u32_e32 v141, vcc, 0, v137, vcc
	s_mov_b32 s1, 0x60000
	v_lshl_add_u64 v[0:1], s[6:7], 1, v[0:1]
	v_lshlrev_b32_e32 v40, 4, v178
	v_mov_b32_e32 v41, v173
	v_add_co_u32_e32 v142, vcc, s1, v136
	v_lshl_add_u64 v[144:145], v[0:1], 0, v[40:41]
	s_nop 0
	v_addc_co_u32_e32 v143, vcc, 0, v137, vcc
	v_add_co_u32_e32 v20, vcc, s21, v144
	global_load_dwordx4 v[0:3], v[138:139], off
	global_load_dwordx4 v[4:7], v[140:141], off
	v_addc_co_u32_e32 v21, vcc, 0, v145, vcc
	v_add_co_u32_e32 v24, vcc, s18, v144
	global_load_dwordx4 v[8:11], v[136:137], off
	global_load_dwordx4 v[12:15], v[144:145], off
	v_addc_co_u32_e32 v25, vcc, 0, v145, vcc
	s_waitcnt vmcnt(5)
	v_add_co_u32_e32 v28, vcc, s37, v144
	global_load_dwordx4 v[16:19], v[142:143], off
	s_nop 0
	global_load_dwordx4 v[20:23], v[20:21], off
	v_addc_co_u32_e32 v29, vcc, 0, v145, vcc
	global_load_dwordx4 v[24:27], v[24:25], off
	s_nop 0
	global_load_dwordx4 v[28:31], v[28:29], off
	s_mov_b32 s1, 0xb0000
	v_add_co_u32_e32 v36, vcc, s1, v144
	s_waitcnt vmcnt(63) expcnt(7) lgkmcnt(15)
	s_barrier
	global_load_dwordx4 v[32:35], v[136:137], off offset:128
	v_addc_co_u32_e32 v37, vcc, 0, v145, vcc
	global_load_dwordx4 v[36:39], v[36:37], off
	v_bfe_u32 v44, v177, 5, 1
	v_lshrrev_b32_e32 v41, 2, v177
	v_ashrrev_i32_e32 v45, 1, v177
	v_and_b32_e32 v46, 0xd0, v177
	v_lshlrev_b32_e32 v47, 2, v177
	v_lshlrev_b32_e32 v176, 3, v44
	s_movk_i32 s7, 0x90
	v_and_b32_e32 v179, 0xffffff80, v45
	v_and_or_b32 v45, v47, 12, v46
	v_and_or_b32 v47, v41, 3, v176
	v_mad_u64_u32 v[40:41], s[12:13], v43, s16, v[40:41]
	v_mad_u64_u32 v[42:43], s[12:13], v42, s7, v[172:173]
	v_add_u32_e32 v151, 0, v42
	v_add_u32_e32 v152, 0, v40
	s_mov_b32 s1, 0x108000
	v_or_b32_e32 v46, v179, v178
	v_mul_u32_u24_e32 v153, 0x240, v47
	v_lshlrev_b32_e32 v170, 1, v45
	v_mul_lo_u32 v171, v46, s7
	v_lshlrev_b32_e32 v172, 4, v44
	v_add3_u32 v149, 0, v153, v170
	v_add3_u32 v148, 0, v171, v172
	v_add_u32_e32 v150, 0x9000, v149
	s_add_i32 s8, s8, s10
	s_waitcnt vmcnt(7)
	ds_write_b128 v151, v[8:11]
	ds_write_b128 v151, v[0:3] offset:9216
	ds_write_b128 v151, v[4:7] offset:18432
	s_waitcnt vmcnt(5)
	ds_write_b128 v151, v[16:19] offset:27648
	ds_write_b128 v152, v[12:15] offset:36864
	s_waitcnt vmcnt(4)
	ds_write_b128 v152, v[20:23] offset:46080
	s_waitcnt vmcnt(3)
	ds_write_b128 v152, v[24:27] offset:55296
	s_waitcnt vmcnt(2)
	ds_write_b128 v152, v[28:31] offset:64512
	v_add_co_u32_e32 v0, vcc, s38, v144
	global_load_dwordx4 v[128:131], v[138:139], off offset:128
	global_load_dwordx4 v[132:135], v[140:141], off offset:128
	global_load_dwordx4 v[154:157], v[142:143], off offset:128
	v_addc_co_u32_e32 v1, vcc, 0, v145, vcc
	global_load_dwordx4 v[158:161], v[0:1], off
	v_add_co_u32_e32 v0, vcc, s1, v144
	s_add_i32 s1, 0, 0x12000
	s_nop 0
	v_addc_co_u32_e32 v1, vcc, 0, v145, vcc
	v_add_co_u32_e32 v2, vcc, s39, v144
	v_add_u32_e32 v147, s1, v42
	s_nop 0
	v_addc_co_u32_e32 v3, vcc, 0, v145, vcc
	global_load_dwordx4 v[162:165], v[0:1], off
	global_load_dwordx4 v[166:169], v[2:3], off
	s_waitcnt lgkmcnt(0)
	s_barrier
	ds_read_b64_tr_b16 v[0:1], v149 offset:36864
	ds_read_b64_tr_b16 v[2:3], v149 offset:39168
	ds_read_b128 v[4:7], v148
	ds_read_b128 v[8:11], v148 offset:4608
	ds_read_b64_tr_b16 v[18:19], v149 offset:39232
	ds_read_b64_tr_b16 v[16:17], v149 offset:36928
	s_waitcnt lgkmcnt(3)
	v_mfma_f32_32x32x16_bf16 v[112:127], v[0:3], v[4:7], 0
	ds_read_b128 v[12:15], v148 offset:9216
	ds_read_b128 v[20:23], v148 offset:13824
	v_add_u32_e32 v146, s1, v40
	s_waitcnt vmcnt(7)
	ds_write_b128 v147, v[32:35]
	s_waitcnt vmcnt(6)
	ds_write_b128 v146, v[36:39] offset:36864
	v_add3_u32 v172, s1, v171, v172
	s_cmpk_gt_i32 s8, 0x15f
	s_waitcnt lgkmcnt(4)
	v_mfma_f32_32x32x16_bf16 v[96:111], v[16:19], v[4:7], 0
	ds_read_b64_tr_b16 v[24:25], v149 offset:46080
	ds_read_b64_tr_b16 v[26:27], v149 offset:48384
	ds_read_b128 v[4:7], v148 offset:32
	ds_read_b128 v[28:31], v148 offset:4640
	ds_read_b64_tr_b16 v[182:183], v149 offset:48448
	ds_read_b64_tr_b16 v[180:181], v149 offset:46144
	s_waitcnt lgkmcnt(9)
	v_mfma_f32_32x32x16_bf16 v[32:47], v[0:3], v[12:15], 0
	v_mfma_f32_32x32x16_bf16 v[48:63], v[16:19], v[12:15], 0
	s_waitcnt lgkmcnt(3)
	v_mfma_f32_32x32x16_bf16 v[112:127], v[24:27], v[4:7], v[112:127]
	s_waitcnt lgkmcnt(0)
	v_mfma_f32_32x32x16_bf16 v[96:111], v[180:183], v[4:7], v[96:111]
	ds_read_b128 v[4:7], v148 offset:9248
	ds_read_b128 v[184:187], v148 offset:13856
	s_waitcnt vmcnt(5)
	ds_write_b128 v147, v[128:131] offset:9216
	s_waitcnt vmcnt(2)
	ds_write_b128 v146, v[158:161] offset:46080
	v_mfma_f32_32x32x16_bf16 v[80:95], v[0:3], v[8:11], 0
	v_mfma_f32_32x32x16_bf16 v[64:79], v[16:19], v[8:11], 0
	s_waitcnt lgkmcnt(3)
; DI f32x16 mfma32(bf16x8 a, bf16x8 b, f32x16 c) { return __builtin_amdgcn_mfma_f32_32x32x16_bf16(a, b, c, 0, 0, 0); }
; DI s16x4 tr_read(const char* p) { bfx4 r = __builtin_amdgcn_ds_read_tr16_b64_v4bf16((LDS_AS bfx4*)p); return __builtin_bit_cast(s16x4, r); }
; DI bf16x8 cat8(s16x4 lo, s16x4 hi) { return __builtin_shufflevector(lo, hi, 0, 1, 2, 3, 4, 5, 6, 7); }
; template <int BM, class Epi>
; DI void gemm_tile(const bf16_t* __restrict__ A, int lda, const bf16_t* __restrict__ B, int ldb, int K, int row0, int col0, const Epi& epi, char* smem) {
;     ...
;     for (int kt = 0; kt < nk; ++kt) {
;         const char* cur = smem + (kt & 1) * GSTAGE;
;         char* nxt = smem + ((kt & 1) ^ 1) * GSTAGE;
;         const bool w1 = kt + 1 < nk, l2 = kt + 2 < nk;
;         const bf16_t* a2 = ag + (size_t)(kt + 2) * 64; const bf16_t* b2 = bg + (size_t)(kt + 2) * 64 * ldb;
; #pragma unroll
;         for (int s = 0; s < 4; ++s) {
;             bf16x8 xf[MI], wf[2];
; #pragma unroll
;             for (int mi = 0; mi < MI; ++mi) xf[mi] = *(const bf16x8*)(cur + xoff + mi * 32 * GA_S + s * 32);
; #pragma unroll
;             for (int ni = 0; ni < 2; ++ni) {
;                 const char* wp = cur + woff + s * 16 * GB_S + ni * 64;
;                 wf[ni] = cat8(tr_read(wp), tr_read(wp + 4 * GB_S));
;             }
; #pragma unroll
;             for (int mi = 0; mi < MI; ++mi)
; #pragma unroll
;                 for (int ni = 0; ni < 2; ++ni) acc[mi][ni] = mfma32(wf[ni], xf[mi], acc[mi][ni]);
;             if (w1) {
;                 if (s < NA_) *(u32x4*)(nxt + aw + 64 * s * GA_S) = ra[s];
;                 *(u32x4*)(nxt + bw + 16 * s * GB_S) = rb[s];
;             }
;             if (l2) {
;                 if (s < NA_) ra[s] = *(const u32x4*)(a2 + (size_t)(64 * s) * lda);
;                 rb[s] = *(const u32x4*)(b2 + (size_t)(16 * s) * ldb);
;             }
;         }
;         __syncthreads();
;     }
	v_mfma_f32_32x32x16_bf16 v[32:47], v[24:27], v[4:7], v[32:47]
	v_mfma_f32_32x32x16_bf16 v[48:63], v[180:183], v[4:7], v[48:63]
	v_mfma_f32_32x32x16_bf16 v[0:15], v[0:3], v[20:23], 0
	v_mfma_f32_32x32x16_bf16 v[80:95], v[24:27], v[28:31], v[80:95]
	v_mfma_f32_32x32x16_bf16 v[64:79], v[180:183], v[28:31], v[64:79]
	s_waitcnt lgkmcnt(2)
	v_mfma_f32_32x32x16_bf16 v[0:15], v[24:27], v[184:187], v[0:15]
	v_mfma_f32_32x32x16_bf16 v[16:31], v[16:19], v[20:23], 0
	v_mfma_f32_32x32x16_bf16 v[16:31], v[180:183], v[184:187], v[16:31]
	ds_read_b64_tr_b16 v[128:129], v149 offset:55296
	ds_read_b64_tr_b16 v[130:131], v149 offset:57600
	ds_read_b64_tr_b16 v[160:161], v149 offset:57664
	ds_read_b64_tr_b16 v[158:159], v149 offset:55360
	ds_read_b128 v[180:183], v148 offset:64
	ds_read_b128 v[184:187], v148 offset:4672
	s_waitcnt lgkmcnt(1)
	v_mfma_f32_32x32x16_bf16 v[112:127], v[128:131], v[180:183], v[112:127]
	v_mfma_f32_32x32x16_bf16 v[96:111], v[158:161], v[180:183], v[96:111]
	s_waitcnt lgkmcnt(0)
	v_mfma_f32_32x32x16_bf16 v[80:95], v[128:131], v[184:187], v[80:95]
	v_mfma_f32_32x32x16_bf16 v[64:79], v[158:161], v[184:187], v[64:79]
	ds_read_b128 v[180:183], v148 offset:9280
	ds_read_b128 v[184:187], v148 offset:13888
	ds_write_b128 v147, v[132:135] offset:18432
	s_waitcnt vmcnt(1)
	ds_write_b128 v146, v[162:165] offset:55296
	s_waitcnt lgkmcnt(3)
	v_mfma_f32_32x32x16_bf16 v[32:47], v[128:131], v[180:183], v[32:47]
	v_mfma_f32_32x32x16_bf16 v[48:63], v[158:161], v[180:183], v[48:63]
	s_waitcnt lgkmcnt(2)
	v_mfma_f32_32x32x16_bf16 v[0:15], v[128:131], v[184:187], v[0:15]
	v_mfma_f32_32x32x16_bf16 v[16:31], v[158:161], v[184:187], v[16:31]
	ds_read_b64_tr_b16 v[128:129], v149 offset:64512
	ds_read_b64_tr_b16 v[130:131], v150 offset:29952
	ds_read_b64_tr_b16 v[134:135], v150 offset:30016
	ds_read_b64_tr_b16 v[132:133], v149 offset:64576
	ds_read_b128 v[158:161], v148 offset:96
	ds_read_b128 v[162:165], v148 offset:4704
	s_waitcnt lgkmcnt(1)
	v_mfma_f32_32x32x16_bf16 v[112:127], v[128:131], v[158:161], v[112:127]
	v_mfma_f32_32x32x16_bf16 v[96:111], v[132:135], v[158:161], v[96:111]
	s_waitcnt lgkmcnt(0)
	v_mfma_f32_32x32x16_bf16 v[80:95], v[128:131], v[162:165], v[80:95]
	v_mfma_f32_32x32x16_bf16 v[64:79], v[132:135], v[162:165], v[64:79]
	ds_read_b128 v[158:161], v148 offset:9312
	ds_read_b128 v[162:165], v148 offset:13920
	ds_write_b128 v147, v[154:157] offset:27648
	s_waitcnt vmcnt(0)
	ds_write_b128 v146, v[166:169] offset:64512
	v_add3_u32 v156, s1, v153, v170
	v_add_u32_e32 v157, 0x9000, v156
	s_mov_b32 s1, 0x210000
	s_waitcnt lgkmcnt(3)
	v_mfma_f32_32x32x16_bf16 v[32:47], v[128:131], v[158:161], v[32:47]
	s_waitcnt lgkmcnt(2)
	v_mfma_f32_32x32x16_bf16 v[0:15], v[128:131], v[162:165], v[0:15]
	v_add_co_u32_e32 v128, vcc, s35, v144
	s_nop 1
	v_addc_co_u32_e32 v129, vcc, 0, v145, vcc
	v_add_co_u32_e32 v130, vcc, s40, v144
	v_mfma_f32_32x32x16_bf16 v[48:63], v[132:135], v[158:161], v[48:63]
	s_nop 0
	v_addc_co_u32_e32 v131, vcc, 0, v145, vcc
	v_add_co_u32_e32 v154, vcc, s41, v144
	s_nop 1
	v_addc_co_u32_e32 v155, vcc, 0, v145, vcc
	v_add_co_u32_e32 v166, vcc, s42, v144
	v_mfma_f32_32x32x16_bf16 v[16:31], v[132:135], v[162:165], v[16:31]
	s_nop 0
	v_addc_co_u32_e32 v167, vcc, 0, v145, vcc
	global_load_dwordx4 v[132:135], v[128:129], off
	global_load_dwordx4 v[158:161], v[130:131], off
	global_load_dwordx4 v[162:165], v[154:155], off
	s_nop 0
	global_load_dwordx4 v[128:131], v[166:167], off
	s_nop 0
	global_load_dwordx4 v[166:169], v[136:137], off offset:256
	global_load_dwordx4 v[180:183], v[138:139], off offset:256
	global_load_dwordx4 v[184:187], v[140:141], off offset:256
	global_load_dwordx4 v[188:191], v[142:143], off offset:256
	s_waitcnt lgkmcnt(0)
	s_barrier
	ds_read_b64_tr_b16 v[234:235], v156 offset:36864
	ds_read_b64_tr_b16 v[236:237], v156 offset:39168
	ds_read_b128 v[218:221], v172
	ds_read_b64_tr_b16 v[238:239], v156 offset:36928
	ds_read_b64_tr_b16 v[240:241], v156 offset:39232
	ds_read_b128 v[222:225], v172 offset:4608
	ds_read_b128 v[226:229], v172 offset:9216
	ds_read_b128 v[230:233], v172 offset:13824
	s_waitcnt lgkmcnt(5)
	v_mfma_f32_32x32x16_bf16 v[112:127], v[234:237], v[218:221], v[112:127]
	ds_read_b64_tr_b16 v[242:243], v156 offset:46080
	ds_read_b64_tr_b16 v[244:245], v156 offset:48384
	ds_read_b64_tr_b16 v[246:247], v156 offset:46144
	ds_read_b64_tr_b16 v[248:249], v156 offset:48448
	s_waitcnt lgkmcnt(7)
	v_mfma_f32_32x32x16_bf16 v[96:111], v[238:241], v[218:221], v[96:111]
	ds_read_b128 v[218:221], v172 offset:32
	s_waitcnt lgkmcnt(7)
	v_mfma_f32_32x32x16_bf16 v[80:95], v[234:237], v[222:225], v[80:95]
	v_mfma_f32_32x32x16_bf16 v[64:79], v[238:241], v[222:225], v[64:79]
	ds_read_b128 v[222:225], v172 offset:4640
	s_waitcnt vmcnt(3)
	ds_write_b128 v151, v[166:169]
	ds_write_b128 v152, v[132:135] offset:36864
	s_waitcnt lgkmcnt(9)
	v_mfma_f32_32x32x16_bf16 v[32:47], v[234:237], v[226:229], v[32:47]
	v_mfma_f32_32x32x16_bf16 v[48:63], v[238:241], v[226:229], v[48:63]
	ds_read_b128 v[226:229], v172 offset:9248
	s_waitcnt lgkmcnt(9)
	v_mfma_f32_32x32x16_bf16 v[0:15], v[234:237], v[230:233], v[0:15]
	v_mfma_f32_32x32x16_bf16 v[16:31], v[238:241], v[230:233], v[16:31]
	ds_read_b128 v[230:233], v172 offset:13856
	s_waitcnt lgkmcnt(5)
	v_mfma_f32_32x32x16_bf16 v[112:127], v[242:245], v[218:221], v[112:127]
	ds_read_b64_tr_b16 v[234:235], v156 offset:55296
	ds_read_b64_tr_b16 v[236:237], v156 offset:57600
	ds_read_b64_tr_b16 v[238:239], v156 offset:55360
	ds_read_b64_tr_b16 v[240:241], v156 offset:57664
	v_mfma_f32_32x32x16_bf16 v[96:111], v[246:249], v[218:221], v[96:111]
	ds_read_b128 v[218:221], v172 offset:64
	s_waitcnt lgkmcnt(9)
; DI f32x16 mfma32(bf16x8 a, bf16x8 b, f32x16 c) { return __builtin_amdgcn_mfma_f32_32x32x16_bf16(a, b, c, 0, 0, 0); }
; DI s16x4 tr_read(const char* p) { bfx4 r = __builtin_amdgcn_ds_read_tr16_b64_v4bf16((LDS_AS bfx4*)p); return __builtin_bit_cast(s16x4, r); }
; DI bf16x8 cat8(s16x4 lo, s16x4 hi) { return __builtin_shufflevector(lo, hi, 0, 1, 2, 3, 4, 5, 6, 7); }
; template <int BM, class Epi>
; DI void gemm_tile(const bf16_t* __restrict__ A, int lda, const bf16_t* __restrict__ B, int ldb, int K, int row0, int col0, const Epi& epi, char* smem) {
;     ...
;     for (int kt = 0; kt < nk; ++kt) {
;         const char* cur = smem + (kt & 1) * GSTAGE;
;         char* nxt = smem + ((kt & 1) ^ 1) * GSTAGE;
;         const bool w1 = kt + 1 < nk, l2 = kt + 2 < nk;
;         const bf16_t* a2 = ag + (size_t)(kt + 2) * 64; const bf16_t* b2 = bg + (size_t)(kt + 2) * 64 * ldb;
; #pragma unroll
;         for (int s = 0; s < 4; ++s) {
;             bf16x8 xf[MI], wf[2];
; #pragma unroll
;             for (int mi = 0; mi < MI; ++mi) xf[mi] = *(const bf16x8*)(cur + xoff + mi * 32 * GA_S + s * 32);
; #pragma unroll
;             for (int ni = 0; ni < 2; ++ni) {
;                 const char* wp = cur + woff + s * 16 * GB_S + ni * 64;
;                 wf[ni] = cat8(tr_read(wp), tr_read(wp + 4 * GB_S));
;             }
; #pragma unroll
;             for (int mi = 0; mi < MI; ++mi)
; #pragma unroll
;                 for (int ni = 0; ni < 2; ++ni) acc[mi][ni] = mfma32(wf[ni], xf[mi], acc[mi][ni]);
;             if (w1) {
;                 if (s < NA_) *(u32x4*)(nxt + aw + 64 * s * GA_S) = ra[s];
;                 *(u32x4*)(nxt + bw + 16 * s * GB_S) = rb[s];
;             }
;             if (l2) {
;                 if (s < NA_) ra[s] = *(const u32x4*)(a2 + (size_t)(64 * s) * lda);
;                 rb[s] = *(const u32x4*)(b2 + (size_t)(16 * s) * ldb);
;             }
;         }
;         __syncthreads();
;     }
	v_mfma_f32_32x32x16_bf16 v[80:95], v[242:245], v[222:225], v[80:95]
	v_mfma_f32_32x32x16_bf16 v[64:79], v[246:249], v[222:225], v[64:79]
	ds_read_b128 v[222:225], v172 offset:4672
	s_waitcnt vmcnt(2)
	ds_write_b128 v151, v[180:183] offset:9216
	ds_write_b128 v152, v[158:161] offset:46080
	s_waitcnt lgkmcnt(9)
	v_mfma_f32_32x32x16_bf16 v[32:47], v[242:245], v[226:229], v[32:47]
	v_mfma_f32_32x32x16_bf16 v[48:63], v[246:249], v[226:229], v[48:63]
	ds_read_b128 v[226:229], v172 offset:9280
	s_waitcnt lgkmcnt(9)
	v_mfma_f32_32x32x16_bf16 v[0:15], v[242:245], v[230:233], v[0:15]
	v_mfma_f32_32x32x16_bf16 v[16:31], v[246:249], v[230:233], v[16:31]
	ds_read_b128 v[230:233], v172 offset:13888
	s_waitcnt lgkmcnt(5)
	v_mfma_f32_32x32x16_bf16 v[112:127], v[234:237], v[218:221], v[112:127]
	ds_read_b64_tr_b16 v[242:243], v156 offset:64512
	ds_read_b64_tr_b16 v[244:245], v157 offset:29952
	ds_read_b64_tr_b16 v[246:247], v156 offset:64576
	ds_read_b64_tr_b16 v[248:249], v157 offset:30016
	v_mfma_f32_32x32x16_bf16 v[96:111], v[238:241], v[218:221], v[96:111]
	ds_read_b128 v[218:221], v172 offset:96
	s_waitcnt lgkmcnt(9)
	v_mfma_f32_32x32x16_bf16 v[80:95], v[234:237], v[222:225], v[80:95]
	v_mfma_f32_32x32x16_bf16 v[64:79], v[238:241], v[222:225], v[64:79]
	ds_read_b128 v[222:225], v172 offset:4704
	s_waitcnt vmcnt(1)
	ds_write_b128 v151, v[184:187] offset:18432
	ds_write_b128 v152, v[162:165] offset:55296
	s_waitcnt lgkmcnt(9)
	v_mfma_f32_32x32x16_bf16 v[32:47], v[234:237], v[226:229], v[32:47]
	v_mfma_f32_32x32x16_bf16 v[48:63], v[238:241], v[226:229], v[48:63]
	ds_read_b128 v[226:229], v172 offset:9312
	s_waitcnt lgkmcnt(9)
	v_mfma_f32_32x32x16_bf16 v[0:15], v[234:237], v[230:233], v[0:15]
	v_mfma_f32_32x32x16_bf16 v[16:31], v[238:241], v[230:233], v[16:31]
	ds_read_b128 v[230:233], v172 offset:13920
	s_waitcnt lgkmcnt(5)
	v_mfma_f32_32x32x16_bf16 v[112:127], v[242:245], v[218:221], v[112:127]
	v_mfma_f32_32x32x16_bf16 v[96:111], v[246:249], v[218:221], v[96:111]
	s_waitcnt lgkmcnt(4)
	v_mfma_f32_32x32x16_bf16 v[80:95], v[242:245], v[222:225], v[80:95]
	v_mfma_f32_32x32x16_bf16 v[64:79], v[246:249], v[222:225], v[64:79]
	s_waitcnt vmcnt(0)
	ds_write_b128 v151, v[188:191] offset:27648
	ds_write_b128 v152, v[128:131] offset:64512
	s_waitcnt lgkmcnt(3)
	v_mfma_f32_32x32x16_bf16 v[32:47], v[242:245], v[226:229], v[32:47]
	v_mfma_f32_32x32x16_bf16 v[48:63], v[246:249], v[226:229], v[48:63]
	s_waitcnt lgkmcnt(2)
	v_mfma_f32_32x32x16_bf16 v[0:15], v[242:245], v[230:233], v[0:15]
	v_mfma_f32_32x32x16_bf16 v[16:31], v[246:249], v[230:233], v[16:31]
	v_add_co_u32_e32 v128, vcc, s1, v144
	s_mov_b32 s1, 0x2c0000
	s_nop 0
	v_addc_co_u32_e32 v129, vcc, 0, v145, vcc
	v_add_co_u32_e32 v130, vcc, s60, v144
	s_nop 1
	v_addc_co_u32_e32 v131, vcc, 0, v145, vcc
	v_add_co_u32_e32 v154, vcc, s43, v144
	s_nop 1
	v_addc_co_u32_e32 v155, vcc, 0, v145, vcc
	v_add_co_u32_e32 v166, vcc, s61, v144
	s_nop 1
	v_addc_co_u32_e32 v167, vcc, 0, v145, vcc
	global_load_dwordx4 v[132:135], v[128:129], off
	global_load_dwordx4 v[158:161], v[130:131], off
	global_load_dwordx4 v[162:165], v[154:155], off
	s_nop 0
	global_load_dwordx4 v[128:131], v[166:167], off
	s_nop 0
	global_load_dwordx4 v[166:169], v[136:137], off offset:384
	global_load_dwordx4 v[180:183], v[138:139], off offset:384
	global_load_dwordx4 v[184:187], v[140:141], off offset:384
	global_load_dwordx4 v[188:191], v[142:143], off offset:384
	s_waitcnt lgkmcnt(0)
	s_barrier
	ds_read_b64_tr_b16 v[234:235], v149 offset:36864
	ds_read_b64_tr_b16 v[236:237], v149 offset:39168
	ds_read_b128 v[218:221], v148
	ds_read_b64_tr_b16 v[238:239], v149 offset:36928
	ds_read_b64_tr_b16 v[240:241], v149 offset:39232
	ds_read_b128 v[222:225], v148 offset:4608
	ds_read_b128 v[226:229], v148 offset:9216
	ds_read_b128 v[230:233], v148 offset:13824
	s_waitcnt lgkmcnt(5)
	v_mfma_f32_32x32x16_bf16 v[112:127], v[234:237], v[218:221], v[112:127]
	ds_read_b64_tr_b16 v[242:243], v149 offset:46080
	ds_read_b64_tr_b16 v[244:245], v149 offset:48384
	ds_read_b64_tr_b16 v[246:247], v149 offset:46144
	ds_read_b64_tr_b16 v[248:249], v149 offset:48448
	s_waitcnt lgkmcnt(7)
	v_mfma_f32_32x32x16_bf16 v[96:111], v[238:241], v[218:221], v[96:111]
	ds_read_b128 v[218:221], v148 offset:32
	s_waitcnt lgkmcnt(7)
	v_mfma_f32_32x32x16_bf16 v[80:95], v[234:237], v[222:225], v[80:95]
	v_mfma_f32_32x32x16_bf16 v[64:79], v[238:241], v[222:225], v[64:79]
	ds_read_b128 v[222:225], v148 offset:4640
	s_waitcnt vmcnt(3)
	ds_write_b128 v147, v[166:169]
	ds_write_b128 v146, v[132:135] offset:36864
	s_waitcnt lgkmcnt(9)
	v_mfma_f32_32x32x16_bf16 v[32:47], v[234:237], v[226:229], v[32:47]
	v_mfma_f32_32x32x16_bf16 v[48:63], v[238:241], v[226:229], v[48:63]
	ds_read_b128 v[226:229], v148 offset:9248
	s_waitcnt lgkmcnt(9)
	v_mfma_f32_32x32x16_bf16 v[0:15], v[234:237], v[230:233], v[0:15]
	v_mfma_f32_32x32x16_bf16 v[16:31], v[238:241], v[230:233], v[16:31]
	ds_read_b128 v[230:233], v148 offset:13856
	s_waitcnt lgkmcnt(5)
	v_mfma_f32_32x32x16_bf16 v[112:127], v[242:245], v[218:221], v[112:127]
	ds_read_b64_tr_b16 v[234:235], v149 offset:55296
	ds_read_b64_tr_b16 v[236:237], v149 offset:57600
	ds_read_b64_tr_b16 v[238:239], v149 offset:55360
	ds_read_b64_tr_b16 v[240:241], v149 offset:57664
	v_mfma_f32_32x32x16_bf16 v[96:111], v[246:249], v[218:221], v[96:111]
	ds_read_b128 v[218:221], v148 offset:64
	s_waitcnt lgkmcnt(9)
	v_mfma_f32_32x32x16_bf16 v[80:95], v[242:245], v[222:225], v[80:95]
	v_mfma_f32_32x32x16_bf16 v[64:79], v[246:249], v[222:225], v[64:79]
	ds_read_b128 v[222:225], v148 offset:4672
	s_waitcnt vmcnt(2)
	ds_write_b128 v147, v[180:183] offset:9216
	ds_write_b128 v146, v[158:161] offset:46080
	s_waitcnt lgkmcnt(9)
; DI f32x16 mfma32(bf16x8 a, bf16x8 b, f32x16 c) { return __builtin_amdgcn_mfma_f32_32x32x16_bf16(a, b, c, 0, 0, 0); }
; DI s16x4 tr_read(const char* p) { bfx4 r = __builtin_amdgcn_ds_read_tr16_b64_v4bf16((LDS_AS bfx4*)p); return __builtin_bit_cast(s16x4, r); }
; DI bf16x8 cat8(s16x4 lo, s16x4 hi) { return __builtin_shufflevector(lo, hi, 0, 1, 2, 3, 4, 5, 6, 7); }
; template <int BM, class Epi>
; DI void gemm_tile(const bf16_t* __restrict__ A, int lda, const bf16_t* __restrict__ B, int ldb, int K, int row0, int col0, const Epi& epi, char* smem) {
;     ...
;     for (int kt = 0; kt < nk; ++kt) {
;         const char* cur = smem + (kt & 1) * GSTAGE;
;         char* nxt = smem + ((kt & 1) ^ 1) * GSTAGE;
;         const bool w1 = kt + 1 < nk, l2 = kt + 2 < nk;
;         const bf16_t* a2 = ag + (size_t)(kt + 2) * 64; const bf16_t* b2 = bg + (size_t)(kt + 2) * 64 * ldb;
; #pragma unroll
;         for (int s = 0; s < 4; ++s) {
;             bf16x8 xf[MI], wf[2];
; #pragma unroll
;             for (int mi = 0; mi < MI; ++mi) xf[mi] = *(const bf16x8*)(cur + xoff + mi * 32 * GA_S + s * 32);
; #pragma unroll
;             for (int ni = 0; ni < 2; ++ni) {
;                 const char* wp = cur + woff + s * 16 * GB_S + ni * 64;
;                 wf[ni] = cat8(tr_read(wp), tr_read(wp + 4 * GB_S));
;             }
; #pragma unroll
;             for (int mi = 0; mi < MI; ++mi)
; #pragma unroll
;                 for (int ni = 0; ni < 2; ++ni) acc[mi][ni] = mfma32(wf[ni], xf[mi], acc[mi][ni]);
;             if (w1) {
;                 if (s < NA_) *(u32x4*)(nxt + aw + 64 * s * GA_S) = ra[s];
;                 *(u32x4*)(nxt + bw + 16 * s * GB_S) = rb[s];
;             }
;             if (l2) {
;                 if (s < NA_) ra[s] = *(const u32x4*)(a2 + (size_t)(64 * s) * lda);
;                 rb[s] = *(const u32x4*)(b2 + (size_t)(16 * s) * ldb);
;             }
;         }
;         __syncthreads();
;     }
	v_mfma_f32_32x32x16_bf16 v[32:47], v[242:245], v[226:229], v[32:47]
	v_mfma_f32_32x32x16_bf16 v[48:63], v[246:249], v[226:229], v[48:63]
	ds_read_b128 v[226:229], v148 offset:9280
	s_waitcnt lgkmcnt(9)
	v_mfma_f32_32x32x16_bf16 v[0:15], v[242:245], v[230:233], v[0:15]
	v_mfma_f32_32x32x16_bf16 v[16:31], v[246:249], v[230:233], v[16:31]
	ds_read_b128 v[230:233], v148 offset:13888
	s_waitcnt lgkmcnt(5)
	v_mfma_f32_32x32x16_bf16 v[112:127], v[234:237], v[218:221], v[112:127]
	ds_read_b64_tr_b16 v[242:243], v149 offset:64512
	ds_read_b64_tr_b16 v[244:245], v150 offset:29952
	ds_read_b64_tr_b16 v[246:247], v149 offset:64576
	ds_read_b64_tr_b16 v[248:249], v150 offset:30016
	v_mfma_f32_32x32x16_bf16 v[96:111], v[238:241], v[218:221], v[96:111]
	ds_read_b128 v[218:221], v148 offset:96
	s_waitcnt lgkmcnt(9)
	v_mfma_f32_32x32x16_bf16 v[80:95], v[234:237], v[222:225], v[80:95]
	v_mfma_f32_32x32x16_bf16 v[64:79], v[238:241], v[222:225], v[64:79]
	ds_read_b128 v[222:225], v148 offset:4704
	s_waitcnt vmcnt(1)
	ds_write_b128 v147, v[184:187] offset:18432
	ds_write_b128 v146, v[162:165] offset:55296
	s_waitcnt lgkmcnt(9)
	v_mfma_f32_32x32x16_bf16 v[32:47], v[234:237], v[226:229], v[32:47]
	v_mfma_f32_32x32x16_bf16 v[48:63], v[238:241], v[226:229], v[48:63]
	ds_read_b128 v[226:229], v148 offset:9312
	s_waitcnt lgkmcnt(9)
	v_mfma_f32_32x32x16_bf16 v[0:15], v[234:237], v[230:233], v[0:15]
	v_mfma_f32_32x32x16_bf16 v[16:31], v[238:241], v[230:233], v[16:31]
	ds_read_b128 v[230:233], v148 offset:13920
	s_waitcnt lgkmcnt(5)
	v_mfma_f32_32x32x16_bf16 v[112:127], v[242:245], v[218:221], v[112:127]
	v_mfma_f32_32x32x16_bf16 v[96:111], v[246:249], v[218:221], v[96:111]
	s_waitcnt lgkmcnt(4)
	v_mfma_f32_32x32x16_bf16 v[80:95], v[242:245], v[222:225], v[80:95]
	v_mfma_f32_32x32x16_bf16 v[64:79], v[246:249], v[222:225], v[64:79]
	s_waitcnt vmcnt(0)
	ds_write_b128 v147, v[188:191] offset:27648
	ds_write_b128 v146, v[128:131] offset:64512
	s_waitcnt lgkmcnt(3)
	v_mfma_f32_32x32x16_bf16 v[32:47], v[242:245], v[226:229], v[32:47]
	v_mfma_f32_32x32x16_bf16 v[48:63], v[246:249], v[226:229], v[48:63]
	s_waitcnt lgkmcnt(2)
	v_mfma_f32_32x32x16_bf16 v[0:15], v[242:245], v[230:233], v[0:15]
	v_mfma_f32_32x32x16_bf16 v[16:31], v[246:249], v[230:233], v[16:31]
	v_add_co_u32_e32 v128, vcc, s1, v144
	s_mov_b32 s1, 0x370000
	s_nop 0
	v_addc_co_u32_e32 v129, vcc, 0, v145, vcc
	v_add_co_u32_e32 v130, vcc, s62, v144
	s_nop 1
	v_addc_co_u32_e32 v131, vcc, 0, v145, vcc
	v_add_co_u32_e32 v154, vcc, s63, v144
	s_nop 1
	v_addc_co_u32_e32 v155, vcc, 0, v145, vcc
	v_add_co_u32_e32 v166, vcc, s64, v144
	s_nop 1
	v_addc_co_u32_e32 v167, vcc, 0, v145, vcc
	global_load_dwordx4 v[132:135], v[128:129], off
	global_load_dwordx4 v[158:161], v[130:131], off
	global_load_dwordx4 v[162:165], v[154:155], off
	s_nop 0
	global_load_dwordx4 v[128:131], v[166:167], off
	s_nop 0
	global_load_dwordx4 v[166:169], v[136:137], off offset:512
	global_load_dwordx4 v[180:183], v[138:139], off offset:512
	global_load_dwordx4 v[184:187], v[140:141], off offset:512
	global_load_dwordx4 v[188:191], v[142:143], off offset:512
	s_waitcnt lgkmcnt(0)
	s_barrier
	ds_read_b64_tr_b16 v[234:235], v156 offset:36864
	ds_read_b64_tr_b16 v[236:237], v156 offset:39168
	ds_read_b128 v[218:221], v172
	ds_read_b64_tr_b16 v[238:239], v156 offset:36928
	ds_read_b64_tr_b16 v[240:241], v156 offset:39232
	ds_read_b128 v[222:225], v172 offset:4608
	ds_read_b128 v[226:229], v172 offset:9216
	ds_read_b128 v[230:233], v172 offset:13824
	s_waitcnt lgkmcnt(5)
	v_mfma_f32_32x32x16_bf16 v[112:127], v[234:237], v[218:221], v[112:127]
	ds_read_b64_tr_b16 v[242:243], v156 offset:46080
	ds_read_b64_tr_b16 v[244:245], v156 offset:48384
	ds_read_b64_tr_b16 v[246:247], v156 offset:46144
	ds_read_b64_tr_b16 v[248:249], v156 offset:48448
	s_waitcnt lgkmcnt(7)
	v_mfma_f32_32x32x16_bf16 v[96:111], v[238:241], v[218:221], v[96:111]
	ds_read_b128 v[218:221], v172 offset:32
	s_waitcnt lgkmcnt(7)
	v_mfma_f32_32x32x16_bf16 v[80:95], v[234:237], v[222:225], v[80:95]
	v_mfma_f32_32x32x16_bf16 v[64:79], v[238:241], v[222:225], v[64:79]
	ds_read_b128 v[222:225], v172 offset:4640
	s_waitcnt vmcnt(3)
	ds_write_b128 v151, v[166:169]
	ds_write_b128 v152, v[132:135] offset:36864
	s_waitcnt lgkmcnt(9)
	v_mfma_f32_32x32x16_bf16 v[32:47], v[234:237], v[226:229], v[32:47]
	v_mfma_f32_32x32x16_bf16 v[48:63], v[238:241], v[226:229], v[48:63]
	ds_read_b128 v[226:229], v172 offset:9248
	s_waitcnt lgkmcnt(9)
	v_mfma_f32_32x32x16_bf16 v[0:15], v[234:237], v[230:233], v[0:15]
	v_mfma_f32_32x32x16_bf16 v[16:31], v[238:241], v[230:233], v[16:31]
	ds_read_b128 v[230:233], v172 offset:13856
	s_waitcnt lgkmcnt(5)
	v_mfma_f32_32x32x16_bf16 v[112:127], v[242:245], v[218:221], v[112:127]
	ds_read_b64_tr_b16 v[234:235], v156 offset:55296
	ds_read_b64_tr_b16 v[236:237], v156 offset:57600
	ds_read_b64_tr_b16 v[238:239], v156 offset:55360
	ds_read_b64_tr_b16 v[240:241], v156 offset:57664
	v_mfma_f32_32x32x16_bf16 v[96:111], v[246:249], v[218:221], v[96:111]
	ds_read_b128 v[218:221], v172 offset:64
	s_waitcnt lgkmcnt(9)
	v_mfma_f32_32x32x16_bf16 v[80:95], v[242:245], v[222:225], v[80:95]
	v_mfma_f32_32x32x16_bf16 v[64:79], v[246:249], v[222:225], v[64:79]
	ds_read_b128 v[222:225], v172 offset:4672
	s_waitcnt vmcnt(2)
	ds_write_b128 v151, v[180:183] offset:9216
	ds_write_b128 v152, v[158:161] offset:46080
	s_waitcnt lgkmcnt(9)
	v_mfma_f32_32x32x16_bf16 v[32:47], v[242:245], v[226:229], v[32:47]
	v_mfma_f32_32x32x16_bf16 v[48:63], v[246:249], v[226:229], v[48:63]
	ds_read_b128 v[226:229], v172 offset:9280
	s_waitcnt lgkmcnt(9)
; DI f32x16 mfma32(bf16x8 a, bf16x8 b, f32x16 c) { return __builtin_amdgcn_mfma_f32_32x32x16_bf16(a, b, c, 0, 0, 0); }
; DI s16x4 tr_read(const char* p) { bfx4 r = __builtin_amdgcn_ds_read_tr16_b64_v4bf16((LDS_AS bfx4*)p); return __builtin_bit_cast(s16x4, r); }
; DI bf16x8 cat8(s16x4 lo, s16x4 hi) { return __builtin_shufflevector(lo, hi, 0, 1, 2, 3, 4, 5, 6, 7); }
; template <int BM, class Epi>
; DI void gemm_tile(const bf16_t* __restrict__ A, int lda, const bf16_t* __restrict__ B, int ldb, int K, int row0, int col0, const Epi& epi, char* smem) {
;     ...
;     for (int kt = 0; kt < nk; ++kt) {
;         const char* cur = smem + (kt & 1) * GSTAGE;
;         char* nxt = smem + ((kt & 1) ^ 1) * GSTAGE;
;         const bool w1 = kt + 1 < nk, l2 = kt + 2 < nk;
;         const bf16_t* a2 = ag + (size_t)(kt + 2) * 64; const bf16_t* b2 = bg + (size_t)(kt + 2) * 64 * ldb;
; #pragma unroll
;         for (int s = 0; s < 4; ++s) {
;             bf16x8 xf[MI], wf[2];
; #pragma unroll
;             for (int mi = 0; mi < MI; ++mi) xf[mi] = *(const bf16x8*)(cur + xoff + mi * 32 * GA_S + s * 32);
; #pragma unroll
;             for (int ni = 0; ni < 2; ++ni) {
;                 const char* wp = cur + woff + s * 16 * GB_S + ni * 64;
;                 wf[ni] = cat8(tr_read(wp), tr_read(wp + 4 * GB_S));
;             }
; #pragma unroll
;             for (int mi = 0; mi < MI; ++mi)
; #pragma unroll
;                 for (int ni = 0; ni < 2; ++ni) acc[mi][ni] = mfma32(wf[ni], xf[mi], acc[mi][ni]);
;             if (w1) {
;                 if (s < NA_) *(u32x4*)(nxt + aw + 64 * s * GA_S) = ra[s];
;                 *(u32x4*)(nxt + bw + 16 * s * GB_S) = rb[s];
;             }
;             if (l2) {
;                 if (s < NA_) ra[s] = *(const u32x4*)(a2 + (size_t)(64 * s) * lda);
;                 rb[s] = *(const u32x4*)(b2 + (size_t)(16 * s) * ldb);
;             }
;         }
	v_mfma_f32_32x32x16_bf16 v[0:15], v[242:245], v[230:233], v[0:15]
	v_mfma_f32_32x32x16_bf16 v[16:31], v[246:249], v[230:233], v[16:31]
	ds_read_b128 v[230:233], v172 offset:13888
	s_waitcnt lgkmcnt(5)
	v_mfma_f32_32x32x16_bf16 v[112:127], v[234:237], v[218:221], v[112:127]
	ds_read_b64_tr_b16 v[242:243], v156 offset:64512
	ds_read_b64_tr_b16 v[244:245], v157 offset:29952
	ds_read_b64_tr_b16 v[246:247], v156 offset:64576
	ds_read_b64_tr_b16 v[248:249], v157 offset:30016
	v_mfma_f32_32x32x16_bf16 v[96:111], v[238:241], v[218:221], v[96:111]
	ds_read_b128 v[218:221], v172 offset:96
	s_waitcnt lgkmcnt(9)
	v_mfma_f32_32x32x16_bf16 v[80:95], v[234:237], v[222:225], v[80:95]
	v_mfma_f32_32x32x16_bf16 v[64:79], v[238:241], v[222:225], v[64:79]
	ds_read_b128 v[222:225], v172 offset:4704
	s_waitcnt vmcnt(1)
	ds_write_b128 v151, v[184:187] offset:18432
	ds_write_b128 v152, v[162:165] offset:55296
	s_waitcnt lgkmcnt(9)
	v_mfma_f32_32x32x16_bf16 v[32:47], v[234:237], v[226:229], v[32:47]
	v_mfma_f32_32x32x16_bf16 v[48:63], v[238:241], v[226:229], v[48:63]
	ds_read_b128 v[226:229], v172 offset:9312
	s_waitcnt lgkmcnt(9)
	v_mfma_f32_32x32x16_bf16 v[0:15], v[234:237], v[230:233], v[0:15]
	v_mfma_f32_32x32x16_bf16 v[16:31], v[238:241], v[230:233], v[16:31]
	ds_read_b128 v[230:233], v172 offset:13920
	s_waitcnt lgkmcnt(5)
	v_mfma_f32_32x32x16_bf16 v[112:127], v[242:245], v[218:221], v[112:127]
	v_mfma_f32_32x32x16_bf16 v[96:111], v[246:249], v[218:221], v[96:111]
	s_waitcnt lgkmcnt(4)
	v_mfma_f32_32x32x16_bf16 v[80:95], v[242:245], v[222:225], v[80:95]
	v_mfma_f32_32x32x16_bf16 v[64:79], v[246:249], v[222:225], v[64:79]
	s_waitcnt vmcnt(0)
	ds_write_b128 v151, v[188:191] offset:27648
	ds_write_b128 v152, v[128:131] offset:64512
	s_waitcnt lgkmcnt(3)
	v_mfma_f32_32x32x16_bf16 v[32:47], v[242:245], v[226:229], v[32:47]
	v_mfma_f32_32x32x16_bf16 v[48:63], v[246:249], v[226:229], v[48:63]
	s_waitcnt lgkmcnt(2)
	v_mfma_f32_32x32x16_bf16 v[0:15], v[242:245], v[230:233], v[0:15]
	v_mfma_f32_32x32x16_bf16 v[16:31], v[246:249], v[230:233], v[16:31]
	v_add_co_u32_e32 v128, vcc, s1, v144
	s_mov_b32 s1, 0x580000
	s_nop 0
	v_addc_co_u32_e32 v129, vcc, 0, v145, vcc
	v_add_co_u32_e32 v130, vcc, s65, v144
	s_nop 1
	v_addc_co_u32_e32 v131, vcc, 0, v145, vcc
	v_add_co_u32_e32 v154, vcc, s66, v144
	s_nop 1
	v_addc_co_u32_e32 v155, vcc, 0, v145, vcc
	v_add_co_u32_e32 v166, vcc, s67, v144
	s_nop 1
	v_addc_co_u32_e32 v167, vcc, 0, v145, vcc
	global_load_dwordx4 v[132:135], v[128:129], off
	global_load_dwordx4 v[158:161], v[130:131], off
	global_load_dwordx4 v[162:165], v[154:155], off
	s_nop 0
	global_load_dwordx4 v[128:131], v[166:167], off
	s_nop 0
	global_load_dwordx4 v[166:169], v[136:137], off offset:640
	global_load_dwordx4 v[180:183], v[138:139], off offset:640
	global_load_dwordx4 v[184:187], v[140:141], off offset:640
	global_load_dwordx4 v[188:191], v[142:143], off offset:640
	s_waitcnt lgkmcnt(0)
	s_barrier
	ds_read_b64_tr_b16 v[234:235], v149 offset:36864
	ds_read_b64_tr_b16 v[236:237], v149 offset:39168
	ds_read_b128 v[218:221], v148
	ds_read_b64_tr_b16 v[238:239], v149 offset:36928
	ds_read_b64_tr_b16 v[240:241], v149 offset:39232
	ds_read_b128 v[222:225], v148 offset:4608
	ds_read_b128 v[226:229], v148 offset:9216
	ds_read_b128 v[230:233], v148 offset:13824
	s_waitcnt lgkmcnt(5)
	v_mfma_f32_32x32x16_bf16 v[112:127], v[234:237], v[218:221], v[112:127]
	ds_read_b64_tr_b16 v[242:243], v149 offset:46080
	ds_read_b64_tr_b16 v[244:245], v149 offset:48384
	ds_read_b64_tr_b16 v[246:247], v149 offset:46144
	ds_read_b64_tr_b16 v[248:249], v149 offset:48448
	s_waitcnt lgkmcnt(7)
	v_mfma_f32_32x32x16_bf16 v[96:111], v[238:241], v[218:221], v[96:111]
	ds_read_b128 v[218:221], v148 offset:32
	s_waitcnt lgkmcnt(7)
	v_mfma_f32_32x32x16_bf16 v[80:95], v[234:237], v[222:225], v[80:95]
	v_mfma_f32_32x32x16_bf16 v[64:79], v[238:241], v[222:225], v[64:79]
	ds_read_b128 v[222:225], v148 offset:4640
	s_waitcnt vmcnt(3)
	ds_write_b128 v147, v[166:169]
	ds_write_b128 v146, v[132:135] offset:36864
	s_waitcnt lgkmcnt(9)
	v_mfma_f32_32x32x16_bf16 v[32:47], v[234:237], v[226:229], v[32:47]
	v_mfma_f32_32x32x16_bf16 v[48:63], v[238:241], v[226:229], v[48:63]
	ds_read_b128 v[226:229], v148 offset:9248
	s_waitcnt lgkmcnt(9)
	v_mfma_f32_32x32x16_bf16 v[0:15], v[234:237], v[230:233], v[0:15]
	v_mfma_f32_32x32x16_bf16 v[16:31], v[238:241], v[230:233], v[16:31]
	ds_read_b128 v[230:233], v148 offset:13856
	s_waitcnt lgkmcnt(5)
	v_mfma_f32_32x32x16_bf16 v[112:127], v[242:245], v[218:221], v[112:127]
	ds_read_b64_tr_b16 v[234:235], v149 offset:55296
	ds_read_b64_tr_b16 v[236:237], v149 offset:57600
	ds_read_b64_tr_b16 v[238:239], v149 offset:55360
	ds_read_b64_tr_b16 v[240:241], v149 offset:57664
	v_mfma_f32_32x32x16_bf16 v[96:111], v[246:249], v[218:221], v[96:111]
	ds_read_b128 v[218:221], v148 offset:64
	s_waitcnt lgkmcnt(9)
	v_mfma_f32_32x32x16_bf16 v[80:95], v[242:245], v[222:225], v[80:95]
	v_mfma_f32_32x32x16_bf16 v[64:79], v[246:249], v[222:225], v[64:79]
	ds_read_b128 v[222:225], v148 offset:4672
	s_waitcnt vmcnt(2)
	ds_write_b128 v147, v[180:183] offset:9216
	ds_write_b128 v146, v[158:161] offset:46080
	s_waitcnt lgkmcnt(9)
	v_mfma_f32_32x32x16_bf16 v[32:47], v[242:245], v[226:229], v[32:47]
	v_mfma_f32_32x32x16_bf16 v[48:63], v[246:249], v[226:229], v[48:63]
	ds_read_b128 v[226:229], v148 offset:9280
	s_waitcnt lgkmcnt(9)
	v_mfma_f32_32x32x16_bf16 v[0:15], v[242:245], v[230:233], v[0:15]
	v_mfma_f32_32x32x16_bf16 v[16:31], v[246:249], v[230:233], v[16:31]
	ds_read_b128 v[230:233], v148 offset:13888
	s_waitcnt lgkmcnt(5)
; DI f32x16 mfma32(bf16x8 a, bf16x8 b, f32x16 c) { return __builtin_amdgcn_mfma_f32_32x32x16_bf16(a, b, c, 0, 0, 0); }
; DI s16x4 tr_read(const char* p) { bfx4 r = __builtin_amdgcn_ds_read_tr16_b64_v4bf16((LDS_AS bfx4*)p); return __builtin_bit_cast(s16x4, r); }
; DI bf16x8 cat8(s16x4 lo, s16x4 hi) { return __builtin_shufflevector(lo, hi, 0, 1, 2, 3, 4, 5, 6, 7); }
; template <int BM, class Epi>
; DI void gemm_tile(const bf16_t* __restrict__ A, int lda, const bf16_t* __restrict__ B, int ldb, int K, int row0, int col0, const Epi& epi, char* smem) {
;     ...
;     for (int kt = 0; kt < nk; ++kt) {
;         const char* cur = smem + (kt & 1) * GSTAGE;
;         char* nxt = smem + ((kt & 1) ^ 1) * GSTAGE;
;         const bool w1 = kt + 1 < nk, l2 = kt + 2 < nk;
;         const bf16_t* a2 = ag + (size_t)(kt + 2) * 64; const bf16_t* b2 = bg + (size_t)(kt + 2) * 64 * ldb;
; #pragma unroll
;         for (int s = 0; s < 4; ++s) {
;             bf16x8 xf[MI], wf[2];
; #pragma unroll
;             for (int mi = 0; mi < MI; ++mi) xf[mi] = *(const bf16x8*)(cur + xoff + mi * 32 * GA_S + s * 32);
; #pragma unroll
;             for (int ni = 0; ni < 2; ++ni) {
;                 const char* wp = cur + woff + s * 16 * GB_S + ni * 64;
;                 wf[ni] = cat8(tr_read(wp), tr_read(wp + 4 * GB_S));
;             }
; #pragma unroll
;             for (int mi = 0; mi < MI; ++mi)
; #pragma unroll
;                 for (int ni = 0; ni < 2; ++ni) acc[mi][ni] = mfma32(wf[ni], xf[mi], acc[mi][ni]);
;             if (w1) {
;                 if (s < NA_) *(u32x4*)(nxt + aw + 64 * s * GA_S) = ra[s];
;                 *(u32x4*)(nxt + bw + 16 * s * GB_S) = rb[s];
;             }
;             if (l2) {
;                 if (s < NA_) ra[s] = *(const u32x4*)(a2 + (size_t)(64 * s) * lda);
;                 rb[s] = *(const u32x4*)(b2 + (size_t)(16 * s) * ldb);
;             }
;         }
	v_mfma_f32_32x32x16_bf16 v[112:127], v[234:237], v[218:221], v[112:127]
	ds_read_b64_tr_b16 v[242:243], v149 offset:64512
	ds_read_b64_tr_b16 v[244:245], v150 offset:29952
	ds_read_b64_tr_b16 v[246:247], v149 offset:64576
	ds_read_b64_tr_b16 v[248:249], v150 offset:30016
	v_mfma_f32_32x32x16_bf16 v[96:111], v[238:241], v[218:221], v[96:111]
	ds_read_b128 v[218:221], v148 offset:96
	s_waitcnt lgkmcnt(9)
	v_mfma_f32_32x32x16_bf16 v[80:95], v[234:237], v[222:225], v[80:95]
	v_mfma_f32_32x32x16_bf16 v[64:79], v[238:241], v[222:225], v[64:79]
	ds_read_b128 v[222:225], v148 offset:4704
	s_waitcnt vmcnt(1)
	ds_write_b128 v147, v[184:187] offset:18432
	ds_write_b128 v146, v[162:165] offset:55296
	s_waitcnt lgkmcnt(9)
	v_mfma_f32_32x32x16_bf16 v[32:47], v[234:237], v[226:229], v[32:47]
	v_mfma_f32_32x32x16_bf16 v[48:63], v[238:241], v[226:229], v[48:63]
	ds_read_b128 v[226:229], v148 offset:9312
	s_waitcnt lgkmcnt(9)
	v_mfma_f32_32x32x16_bf16 v[0:15], v[234:237], v[230:233], v[0:15]
	v_mfma_f32_32x32x16_bf16 v[16:31], v[238:241], v[230:233], v[16:31]
	ds_read_b128 v[230:233], v148 offset:13920
	s_waitcnt lgkmcnt(5)
	v_mfma_f32_32x32x16_bf16 v[112:127], v[242:245], v[218:221], v[112:127]
	v_mfma_f32_32x32x16_bf16 v[96:111], v[246:249], v[218:221], v[96:111]
	s_waitcnt lgkmcnt(4)
	v_mfma_f32_32x32x16_bf16 v[80:95], v[242:245], v[222:225], v[80:95]
	v_mfma_f32_32x32x16_bf16 v[64:79], v[246:249], v[222:225], v[64:79]
	s_waitcnt vmcnt(0)
	ds_write_b128 v147, v[188:191] offset:27648
	ds_write_b128 v146, v[128:131] offset:64512
	s_waitcnt lgkmcnt(3)
	v_mfma_f32_32x32x16_bf16 v[32:47], v[242:245], v[226:229], v[32:47]
	v_mfma_f32_32x32x16_bf16 v[48:63], v[246:249], v[226:229], v[48:63]
	s_waitcnt lgkmcnt(2)
	v_mfma_f32_32x32x16_bf16 v[0:15], v[242:245], v[230:233], v[0:15]
	v_mfma_f32_32x32x16_bf16 v[16:31], v[246:249], v[230:233], v[16:31]
	v_add_co_u32_e32 v128, vcc, s68, v144
	s_nop 1
	v_addc_co_u32_e32 v129, vcc, 0, v145, vcc
	v_add_co_u32_e32 v130, vcc, s69, v144
	s_nop 1
	v_addc_co_u32_e32 v131, vcc, 0, v145, vcc
	v_add_co_u32_e32 v154, vcc, s70, v144
	s_nop 1
	v_addc_co_u32_e32 v155, vcc, 0, v145, vcc
	v_add_co_u32_e32 v166, vcc, s71, v144
	s_nop 1
	v_addc_co_u32_e32 v167, vcc, 0, v145, vcc
	global_load_dwordx4 v[132:135], v[128:129], off
	global_load_dwordx4 v[158:161], v[130:131], off
	global_load_dwordx4 v[162:165], v[154:155], off
	s_nop 0
	global_load_dwordx4 v[128:131], v[166:167], off
	s_nop 0
	global_load_dwordx4 v[166:169], v[136:137], off offset:768
	global_load_dwordx4 v[180:183], v[138:139], off offset:768
	global_load_dwordx4 v[184:187], v[140:141], off offset:768
	global_load_dwordx4 v[188:191], v[142:143], off offset:768
	s_waitcnt lgkmcnt(0)
	s_barrier
	ds_read_b64_tr_b16 v[234:235], v156 offset:36864
	ds_read_b64_tr_b16 v[236:237], v156 offset:39168
	ds_read_b128 v[218:221], v172
	ds_read_b64_tr_b16 v[238:239], v156 offset:36928
	ds_read_b64_tr_b16 v[240:241], v156 offset:39232
	ds_read_b128 v[222:225], v172 offset:4608
	ds_read_b128 v[226:229], v172 offset:9216
	ds_read_b128 v[230:233], v172 offset:13824
	s_waitcnt lgkmcnt(5)
	v_mfma_f32_32x32x16_bf16 v[112:127], v[234:237], v[218:221], v[112:127]
	ds_read_b64_tr_b16 v[242:243], v156 offset:46080
	ds_read_b64_tr_b16 v[244:245], v156 offset:48384
	ds_read_b64_tr_b16 v[246:247], v156 offset:46144
	ds_read_b64_tr_b16 v[248:249], v156 offset:48448
	s_waitcnt lgkmcnt(7)
	v_mfma_f32_32x32x16_bf16 v[96:111], v[238:241], v[218:221], v[96:111]
	ds_read_b128 v[218:221], v172 offset:32
	s_waitcnt lgkmcnt(7)
	v_mfma_f32_32x32x16_bf16 v[80:95], v[234:237], v[222:225], v[80:95]
	v_mfma_f32_32x32x16_bf16 v[64:79], v[238:241], v[222:225], v[64:79]
	ds_read_b128 v[222:225], v172 offset:4640
	s_waitcnt vmcnt(3)
	ds_write_b128 v151, v[166:169]
	ds_write_b128 v152, v[132:135] offset:36864
	s_waitcnt lgkmcnt(9)
	v_mfma_f32_32x32x16_bf16 v[32:47], v[234:237], v[226:229], v[32:47]
	v_mfma_f32_32x32x16_bf16 v[48:63], v[238:241], v[226:229], v[48:63]
	ds_read_b128 v[226:229], v172 offset:9248
	s_waitcnt lgkmcnt(9)
	v_mfma_f32_32x32x16_bf16 v[0:15], v[234:237], v[230:233], v[0:15]
	v_mfma_f32_32x32x16_bf16 v[16:31], v[238:241], v[230:233], v[16:31]
	ds_read_b128 v[230:233], v172 offset:13856
	s_waitcnt lgkmcnt(5)
	v_mfma_f32_32x32x16_bf16 v[112:127], v[242:245], v[218:221], v[112:127]
	ds_read_b64_tr_b16 v[234:235], v156 offset:55296
	ds_read_b64_tr_b16 v[236:237], v156 offset:57600
	ds_read_b64_tr_b16 v[238:239], v156 offset:55360
	ds_read_b64_tr_b16 v[240:241], v156 offset:57664
	v_mfma_f32_32x32x16_bf16 v[96:111], v[246:249], v[218:221], v[96:111]
	ds_read_b128 v[218:221], v172 offset:64
	s_waitcnt lgkmcnt(9)
	v_mfma_f32_32x32x16_bf16 v[80:95], v[242:245], v[222:225], v[80:95]
	v_mfma_f32_32x32x16_bf16 v[64:79], v[246:249], v[222:225], v[64:79]
	ds_read_b128 v[222:225], v172 offset:4672
	s_waitcnt vmcnt(2)
	ds_write_b128 v151, v[180:183] offset:9216
	ds_write_b128 v152, v[158:161] offset:46080
	s_waitcnt lgkmcnt(9)
	v_mfma_f32_32x32x16_bf16 v[32:47], v[242:245], v[226:229], v[32:47]
	v_mfma_f32_32x32x16_bf16 v[48:63], v[246:249], v[226:229], v[48:63]
	ds_read_b128 v[226:229], v172 offset:9280
	s_waitcnt lgkmcnt(9)
	v_mfma_f32_32x32x16_bf16 v[0:15], v[242:245], v[230:233], v[0:15]
	v_mfma_f32_32x32x16_bf16 v[16:31], v[246:249], v[230:233], v[16:31]
	ds_read_b128 v[230:233], v172 offset:13888
	s_waitcnt lgkmcnt(5)
	v_mfma_f32_32x32x16_bf16 v[112:127], v[234:237], v[218:221], v[112:127]
	ds_read_b64_tr_b16 v[242:243], v156 offset:64512
	ds_read_b64_tr_b16 v[244:245], v157 offset:29952
	ds_read_b64_tr_b16 v[246:247], v156 offset:64576
	ds_read_b64_tr_b16 v[248:249], v157 offset:30016
	v_mfma_f32_32x32x16_bf16 v[96:111], v[238:241], v[218:221], v[96:111]
	ds_read_b128 v[218:221], v172 offset:96
	s_waitcnt lgkmcnt(9)
; DI f32x16 mfma32(bf16x8 a, bf16x8 b, f32x16 c) { return __builtin_amdgcn_mfma_f32_32x32x16_bf16(a, b, c, 0, 0, 0); }
; DI s16x4 tr_read(const char* p) { bfx4 r = __builtin_amdgcn_ds_read_tr16_b64_v4bf16((LDS_AS bfx4*)p); return __builtin_bit_cast(s16x4, r); }
; DI bf16x8 cat8(s16x4 lo, s16x4 hi) { return __builtin_shufflevector(lo, hi, 0, 1, 2, 3, 4, 5, 6, 7); }
; template <int BM, class Epi>
; DI void gemm_tile(const bf16_t* __restrict__ A, int lda, const bf16_t* __restrict__ B, int ldb, int K, int row0, int col0, const Epi& epi, char* smem) {
;     ...
;     for (int kt = 0; kt < nk; ++kt) {
;         const char* cur = smem + (kt & 1) * GSTAGE;
;         char* nxt = smem + ((kt & 1) ^ 1) * GSTAGE;
;         const bool w1 = kt + 1 < nk, l2 = kt + 2 < nk;
;         const bf16_t* a2 = ag + (size_t)(kt + 2) * 64; const bf16_t* b2 = bg + (size_t)(kt + 2) * 64 * ldb;
; #pragma unroll
;         for (int s = 0; s < 4; ++s) {
;             bf16x8 xf[MI], wf[2];
; #pragma unroll
;             for (int mi = 0; mi < MI; ++mi) xf[mi] = *(const bf16x8*)(cur + xoff + mi * 32 * GA_S + s * 32);
; #pragma unroll
;             for (int ni = 0; ni < 2; ++ni) {
;                 const char* wp = cur + woff + s * 16 * GB_S + ni * 64;
;                 wf[ni] = cat8(tr_read(wp), tr_read(wp + 4 * GB_S));
;             }
; #pragma unroll
;             for (int mi = 0; mi < MI; ++mi)
; #pragma unroll
;                 for (int ni = 0; ni < 2; ++ni) acc[mi][ni] = mfma32(wf[ni], xf[mi], acc[mi][ni]);
;             if (w1) {
;                 if (s < NA_) *(u32x4*)(nxt + aw + 64 * s * GA_S) = ra[s];
;                 *(u32x4*)(nxt + bw + 16 * s * GB_S) = rb[s];
;             }
;             if (l2) {
;                 if (s < NA_) ra[s] = *(const u32x4*)(a2 + (size_t)(64 * s) * lda);
;                 rb[s] = *(const u32x4*)(b2 + (size_t)(16 * s) * ldb);
;             }
;         }
	v_mfma_f32_32x32x16_bf16 v[80:95], v[234:237], v[222:225], v[80:95]
	v_mfma_f32_32x32x16_bf16 v[64:79], v[238:241], v[222:225], v[64:79]
	ds_read_b128 v[222:225], v172 offset:4704
	s_waitcnt vmcnt(1)
	ds_write_b128 v151, v[184:187] offset:18432
	ds_write_b128 v152, v[162:165] offset:55296
	s_waitcnt lgkmcnt(9)
	v_mfma_f32_32x32x16_bf16 v[32:47], v[234:237], v[226:229], v[32:47]
	v_mfma_f32_32x32x16_bf16 v[48:63], v[238:241], v[226:229], v[48:63]
	ds_read_b128 v[226:229], v172 offset:9312
	s_waitcnt lgkmcnt(9)
	v_mfma_f32_32x32x16_bf16 v[0:15], v[234:237], v[230:233], v[0:15]
	v_mfma_f32_32x32x16_bf16 v[16:31], v[238:241], v[230:233], v[16:31]
	ds_read_b128 v[230:233], v172 offset:13920
	s_waitcnt lgkmcnt(5)
	v_mfma_f32_32x32x16_bf16 v[112:127], v[242:245], v[218:221], v[112:127]
	v_mfma_f32_32x32x16_bf16 v[96:111], v[246:249], v[218:221], v[96:111]
	s_waitcnt lgkmcnt(4)
	v_mfma_f32_32x32x16_bf16 v[80:95], v[242:245], v[222:225], v[80:95]
	v_mfma_f32_32x32x16_bf16 v[64:79], v[246:249], v[222:225], v[64:79]
	s_waitcnt vmcnt(0)
	ds_write_b128 v151, v[188:191] offset:27648
	ds_write_b128 v152, v[128:131] offset:64512
	s_waitcnt lgkmcnt(3)
	v_mfma_f32_32x32x16_bf16 v[32:47], v[242:245], v[226:229], v[32:47]
	v_mfma_f32_32x32x16_bf16 v[48:63], v[246:249], v[226:229], v[48:63]
	s_waitcnt lgkmcnt(2)
	v_mfma_f32_32x32x16_bf16 v[0:15], v[242:245], v[230:233], v[0:15]
	v_mfma_f32_32x32x16_bf16 v[16:31], v[246:249], v[230:233], v[16:31]
	v_add_co_u32_e32 v128, vcc, s72, v144
	s_nop 1
	v_addc_co_u32_e32 v129, vcc, 0, v145, vcc
	v_add_co_u32_e32 v130, vcc, s73, v144
	s_nop 1
	v_addc_co_u32_e32 v131, vcc, 0, v145, vcc
	v_add_co_u32_e32 v154, vcc, s74, v144
	s_nop 1
	v_addc_co_u32_e32 v155, vcc, 0, v145, vcc
	v_add_co_u32_e32 v166, vcc, s75, v144
	s_nop 1
	v_addc_co_u32_e32 v167, vcc, 0, v145, vcc
	global_load_dwordx4 v[132:135], v[128:129], off
	global_load_dwordx4 v[158:161], v[130:131], off
	global_load_dwordx4 v[162:165], v[154:155], off
	s_nop 0
	global_load_dwordx4 v[128:131], v[166:167], off
	s_nop 0
	global_load_dwordx4 v[166:169], v[136:137], off offset:896
	global_load_dwordx4 v[180:183], v[138:139], off offset:896
	global_load_dwordx4 v[184:187], v[140:141], off offset:896
	global_load_dwordx4 v[188:191], v[142:143], off offset:896
	s_waitcnt lgkmcnt(0)
	s_barrier
	ds_read_b64_tr_b16 v[234:235], v149 offset:36864
	ds_read_b64_tr_b16 v[236:237], v149 offset:39168
	ds_read_b128 v[218:221], v148
	ds_read_b64_tr_b16 v[238:239], v149 offset:36928
	ds_read_b64_tr_b16 v[240:241], v149 offset:39232
	ds_read_b128 v[222:225], v148 offset:4608
	ds_read_b128 v[226:229], v148 offset:9216
	ds_read_b128 v[230:233], v148 offset:13824
	s_waitcnt lgkmcnt(5)
	v_mfma_f32_32x32x16_bf16 v[112:127], v[234:237], v[218:221], v[112:127]
	ds_read_b64_tr_b16 v[242:243], v149 offset:46080
	ds_read_b64_tr_b16 v[244:245], v149 offset:48384
	ds_read_b64_tr_b16 v[246:247], v149 offset:46144
	ds_read_b64_tr_b16 v[248:249], v149 offset:48448
	s_waitcnt lgkmcnt(7)
	v_mfma_f32_32x32x16_bf16 v[96:111], v[238:241], v[218:221], v[96:111]
	ds_read_b128 v[218:221], v148 offset:32
	s_waitcnt lgkmcnt(7)
	v_mfma_f32_32x32x16_bf16 v[80:95], v[234:237], v[222:225], v[80:95]
	v_mfma_f32_32x32x16_bf16 v[64:79], v[238:241], v[222:225], v[64:79]
	ds_read_b128 v[222:225], v148 offset:4640
	s_waitcnt vmcnt(3)
	ds_write_b128 v147, v[166:169]
	ds_write_b128 v146, v[132:135] offset:36864
	s_waitcnt lgkmcnt(9)
	v_mfma_f32_32x32x16_bf16 v[32:47], v[234:237], v[226:229], v[32:47]
	v_mfma_f32_32x32x16_bf16 v[48:63], v[238:241], v[226:229], v[48:63]
	ds_read_b128 v[226:229], v148 offset:9248
	s_waitcnt lgkmcnt(9)
	v_mfma_f32_32x32x16_bf16 v[0:15], v[234:237], v[230:233], v[0:15]
	v_mfma_f32_32x32x16_bf16 v[16:31], v[238:241], v[230:233], v[16:31]
	ds_read_b128 v[230:233], v148 offset:13856
	s_waitcnt lgkmcnt(5)
	v_mfma_f32_32x32x16_bf16 v[112:127], v[242:245], v[218:221], v[112:127]
	ds_read_b64_tr_b16 v[234:235], v149 offset:55296
	ds_read_b64_tr_b16 v[236:237], v149 offset:57600
	ds_read_b64_tr_b16 v[238:239], v149 offset:55360
	ds_read_b64_tr_b16 v[240:241], v149 offset:57664
	v_mfma_f32_32x32x16_bf16 v[96:111], v[246:249], v[218:221], v[96:111]
	ds_read_b128 v[218:221], v148 offset:64
	s_waitcnt lgkmcnt(9)
	v_mfma_f32_32x32x16_bf16 v[80:95], v[242:245], v[222:225], v[80:95]
	v_mfma_f32_32x32x16_bf16 v[64:79], v[246:249], v[222:225], v[64:79]
	ds_read_b128 v[222:225], v148 offset:4672
	s_waitcnt vmcnt(2)
	ds_write_b128 v147, v[180:183] offset:9216
	ds_write_b128 v146, v[158:161] offset:46080
	s_waitcnt lgkmcnt(9)
	v_mfma_f32_32x32x16_bf16 v[32:47], v[242:245], v[226:229], v[32:47]
	v_mfma_f32_32x32x16_bf16 v[48:63], v[246:249], v[226:229], v[48:63]
	ds_read_b128 v[226:229], v148 offset:9280
	s_waitcnt lgkmcnt(9)
	v_mfma_f32_32x32x16_bf16 v[0:15], v[242:245], v[230:233], v[0:15]
	v_mfma_f32_32x32x16_bf16 v[16:31], v[246:249], v[230:233], v[16:31]
	ds_read_b128 v[230:233], v148 offset:13888
	s_waitcnt lgkmcnt(5)
	v_mfma_f32_32x32x16_bf16 v[112:127], v[234:237], v[218:221], v[112:127]
	ds_read_b64_tr_b16 v[242:243], v149 offset:64512
	ds_read_b64_tr_b16 v[244:245], v150 offset:29952
	ds_read_b64_tr_b16 v[246:247], v149 offset:64576
	ds_read_b64_tr_b16 v[248:249], v150 offset:30016
	v_mfma_f32_32x32x16_bf16 v[96:111], v[238:241], v[218:221], v[96:111]
	ds_read_b128 v[218:221], v148 offset:96
	s_waitcnt lgkmcnt(9)
	v_mfma_f32_32x32x16_bf16 v[80:95], v[234:237], v[222:225], v[80:95]
	v_mfma_f32_32x32x16_bf16 v[64:79], v[238:241], v[222:225], v[64:79]
	ds_read_b128 v[222:225], v148 offset:4704
	s_waitcnt vmcnt(1)
	ds_write_b128 v147, v[184:187] offset:18432
	ds_write_b128 v146, v[162:165] offset:55296
	s_waitcnt lgkmcnt(9)
; DI f32x16 mfma32(bf16x8 a, bf16x8 b, f32x16 c) { return __builtin_amdgcn_mfma_f32_32x32x16_bf16(a, b, c, 0, 0, 0); }
; DI s16x4 tr_read(const char* p) { bfx4 r = __builtin_amdgcn_ds_read_tr16_b64_v4bf16((LDS_AS bfx4*)p); return __builtin_bit_cast(s16x4, r); }
; DI bf16x8 cat8(s16x4 lo, s16x4 hi) { return __builtin_shufflevector(lo, hi, 0, 1, 2, 3, 4, 5, 6, 7); }
; template <int BM, class Epi>
; DI void gemm_tile(const bf16_t* __restrict__ A, int lda, const bf16_t* __restrict__ B, int ldb, int K, int row0, int col0, const Epi& epi, char* smem) {
;     ...
;     for (int kt = 0; kt < nk; ++kt) {
;         const char* cur = smem + (kt & 1) * GSTAGE;
;         char* nxt = smem + ((kt & 1) ^ 1) * GSTAGE;
;         const bool w1 = kt + 1 < nk, l2 = kt + 2 < nk;
;         const bf16_t* a2 = ag + (size_t)(kt + 2) * 64; const bf16_t* b2 = bg + (size_t)(kt + 2) * 64 * ldb;
; #pragma unroll
;         for (int s = 0; s < 4; ++s) {
;             bf16x8 xf[MI], wf[2];
; #pragma unroll
;             for (int mi = 0; mi < MI; ++mi) xf[mi] = *(const bf16x8*)(cur + xoff + mi * 32 * GA_S + s * 32);
; #pragma unroll
;             for (int ni = 0; ni < 2; ++ni) {
;                 const char* wp = cur + woff + s * 16 * GB_S + ni * 64;
;                 wf[ni] = cat8(tr_read(wp), tr_read(wp + 4 * GB_S));
;             }
; #pragma unroll
;             for (int mi = 0; mi < MI; ++mi)
; #pragma unroll
;                 for (int ni = 0; ni < 2; ++ni) acc[mi][ni] = mfma32(wf[ni], xf[mi], acc[mi][ni]);
;             if (w1) {
;                 if (s < NA_) *(u32x4*)(nxt + aw + 64 * s * GA_S) = ra[s];
;                 *(u32x4*)(nxt + bw + 16 * s * GB_S) = rb[s];
;             }
;             if (l2) {
;                 if (s < NA_) ra[s] = *(const u32x4*)(a2 + (size_t)(64 * s) * lda);
;                 rb[s] = *(const u32x4*)(b2 + (size_t)(16 * s) * ldb);
;             }
;         }
	v_mfma_f32_32x32x16_bf16 v[32:47], v[234:237], v[226:229], v[32:47]
	v_mfma_f32_32x32x16_bf16 v[48:63], v[238:241], v[226:229], v[48:63]
	ds_read_b128 v[226:229], v148 offset:9312
	s_waitcnt lgkmcnt(9)
	v_mfma_f32_32x32x16_bf16 v[0:15], v[234:237], v[230:233], v[0:15]
	v_mfma_f32_32x32x16_bf16 v[16:31], v[238:241], v[230:233], v[16:31]
	ds_read_b128 v[230:233], v148 offset:13920
	s_waitcnt lgkmcnt(5)
	v_mfma_f32_32x32x16_bf16 v[112:127], v[242:245], v[218:221], v[112:127]
	v_mfma_f32_32x32x16_bf16 v[96:111], v[246:249], v[218:221], v[96:111]
	s_waitcnt lgkmcnt(4)
	v_mfma_f32_32x32x16_bf16 v[80:95], v[242:245], v[222:225], v[80:95]
	v_mfma_f32_32x32x16_bf16 v[64:79], v[246:249], v[222:225], v[64:79]
	s_waitcnt vmcnt(0)
	ds_write_b128 v147, v[188:191] offset:27648
	ds_write_b128 v146, v[128:131] offset:64512
	s_waitcnt lgkmcnt(3)
	v_mfma_f32_32x32x16_bf16 v[32:47], v[242:245], v[226:229], v[32:47]
	v_mfma_f32_32x32x16_bf16 v[48:63], v[246:249], v[226:229], v[48:63]
	s_waitcnt lgkmcnt(2)
	v_mfma_f32_32x32x16_bf16 v[0:15], v[242:245], v[230:233], v[0:15]
	v_mfma_f32_32x32x16_bf16 v[16:31], v[246:249], v[230:233], v[16:31]
	v_add_co_u32_e32 v128, vcc, s1, v144
	s_mov_b32 s1, 0x630000
	s_nop 0
	v_addc_co_u32_e32 v129, vcc, 0, v145, vcc
	v_add_co_u32_e32 v130, vcc, s84, v144
	s_nop 1
	v_addc_co_u32_e32 v131, vcc, 0, v145, vcc
	v_add_co_u32_e32 v154, vcc, s86, v144
	s_nop 1
	v_addc_co_u32_e32 v155, vcc, 0, v145, vcc
	v_add_co_u32_e32 v166, vcc, s85, v144
	s_nop 1
	v_addc_co_u32_e32 v167, vcc, 0, v145, vcc
	global_load_dwordx4 v[132:135], v[128:129], off
	global_load_dwordx4 v[158:161], v[130:131], off
	global_load_dwordx4 v[162:165], v[154:155], off
	s_nop 0
	global_load_dwordx4 v[128:131], v[166:167], off
	s_nop 0
	global_load_dwordx4 v[166:169], v[136:137], off offset:1024
	global_load_dwordx4 v[180:183], v[138:139], off offset:1024
	global_load_dwordx4 v[184:187], v[140:141], off offset:1024
	global_load_dwordx4 v[188:191], v[142:143], off offset:1024
	s_waitcnt lgkmcnt(0)
	s_barrier
	ds_read_b64_tr_b16 v[234:235], v156 offset:36864
	ds_read_b64_tr_b16 v[236:237], v156 offset:39168
	ds_read_b128 v[218:221], v172
	ds_read_b64_tr_b16 v[238:239], v156 offset:36928
	ds_read_b64_tr_b16 v[240:241], v156 offset:39232
	ds_read_b128 v[222:225], v172 offset:4608
	ds_read_b128 v[226:229], v172 offset:9216
	ds_read_b128 v[230:233], v172 offset:13824
	s_waitcnt lgkmcnt(5)
	v_mfma_f32_32x32x16_bf16 v[112:127], v[234:237], v[218:221], v[112:127]
	ds_read_b64_tr_b16 v[242:243], v156 offset:46080
	ds_read_b64_tr_b16 v[244:245], v156 offset:48384
	ds_read_b64_tr_b16 v[246:247], v156 offset:46144
	ds_read_b64_tr_b16 v[248:249], v156 offset:48448
	s_waitcnt lgkmcnt(7)
	v_mfma_f32_32x32x16_bf16 v[96:111], v[238:241], v[218:221], v[96:111]
	ds_read_b128 v[218:221], v172 offset:32
	s_waitcnt lgkmcnt(7)
	v_mfma_f32_32x32x16_bf16 v[80:95], v[234:237], v[222:225], v[80:95]
	v_mfma_f32_32x32x16_bf16 v[64:79], v[238:241], v[222:225], v[64:79]
	ds_read_b128 v[222:225], v172 offset:4640
	s_waitcnt vmcnt(3)
	ds_write_b128 v151, v[166:169]
	ds_write_b128 v152, v[132:135] offset:36864
	s_waitcnt lgkmcnt(9)
	v_mfma_f32_32x32x16_bf16 v[32:47], v[234:237], v[226:229], v[32:47]
	v_mfma_f32_32x32x16_bf16 v[48:63], v[238:241], v[226:229], v[48:63]
	ds_read_b128 v[226:229], v172 offset:9248
	s_waitcnt lgkmcnt(9)
	v_mfma_f32_32x32x16_bf16 v[0:15], v[234:237], v[230:233], v[0:15]
	v_mfma_f32_32x32x16_bf16 v[16:31], v[238:241], v[230:233], v[16:31]
	ds_read_b128 v[230:233], v172 offset:13856
	s_waitcnt lgkmcnt(5)
	v_mfma_f32_32x32x16_bf16 v[112:127], v[242:245], v[218:221], v[112:127]
	ds_read_b64_tr_b16 v[234:235], v156 offset:55296
	ds_read_b64_tr_b16 v[236:237], v156 offset:57600
	ds_read_b64_tr_b16 v[238:239], v156 offset:55360
	ds_read_b64_tr_b16 v[240:241], v156 offset:57664
	v_mfma_f32_32x32x16_bf16 v[96:111], v[246:249], v[218:221], v[96:111]
	ds_read_b128 v[218:221], v172 offset:64
	s_waitcnt lgkmcnt(9)
	v_mfma_f32_32x32x16_bf16 v[80:95], v[242:245], v[222:225], v[80:95]
	v_mfma_f32_32x32x16_bf16 v[64:79], v[246:249], v[222:225], v[64:79]
	ds_read_b128 v[222:225], v172 offset:4672
	s_waitcnt vmcnt(2)
	ds_write_b128 v151, v[180:183] offset:9216
	ds_write_b128 v152, v[158:161] offset:46080
	s_waitcnt lgkmcnt(9)
	v_mfma_f32_32x32x16_bf16 v[32:47], v[242:245], v[226:229], v[32:47]
	v_mfma_f32_32x32x16_bf16 v[48:63], v[246:249], v[226:229], v[48:63]
	ds_read_b128 v[226:229], v172 offset:9280
	s_waitcnt lgkmcnt(9)
	v_mfma_f32_32x32x16_bf16 v[0:15], v[242:245], v[230:233], v[0:15]
	v_mfma_f32_32x32x16_bf16 v[16:31], v[246:249], v[230:233], v[16:31]
	ds_read_b128 v[230:233], v172 offset:13888
	s_waitcnt lgkmcnt(5)
	v_mfma_f32_32x32x16_bf16 v[112:127], v[234:237], v[218:221], v[112:127]
	ds_read_b64_tr_b16 v[242:243], v156 offset:64512
	ds_read_b64_tr_b16 v[244:245], v157 offset:29952
	ds_read_b64_tr_b16 v[246:247], v156 offset:64576
	ds_read_b64_tr_b16 v[248:249], v157 offset:30016
	v_mfma_f32_32x32x16_bf16 v[96:111], v[238:241], v[218:221], v[96:111]
	ds_read_b128 v[218:221], v172 offset:96
	s_waitcnt lgkmcnt(9)
	v_mfma_f32_32x32x16_bf16 v[80:95], v[234:237], v[222:225], v[80:95]
	v_mfma_f32_32x32x16_bf16 v[64:79], v[238:241], v[222:225], v[64:79]
	ds_read_b128 v[222:225], v172 offset:4704
	s_waitcnt vmcnt(1)
	ds_write_b128 v151, v[184:187] offset:18432
	ds_write_b128 v152, v[162:165] offset:55296
	s_waitcnt lgkmcnt(9)
	v_mfma_f32_32x32x16_bf16 v[32:47], v[234:237], v[226:229], v[32:47]
	v_mfma_f32_32x32x16_bf16 v[48:63], v[238:241], v[226:229], v[48:63]
	ds_read_b128 v[226:229], v172 offset:9312
	s_waitcnt lgkmcnt(9)
; DI f32x16 mfma32(bf16x8 a, bf16x8 b, f32x16 c) { return __builtin_amdgcn_mfma_f32_32x32x16_bf16(a, b, c, 0, 0, 0); }
; DI s16x4 tr_read(const char* p) { bfx4 r = __builtin_amdgcn_ds_read_tr16_b64_v4bf16((LDS_AS bfx4*)p); return __builtin_bit_cast(s16x4, r); }
; DI bf16x8 cat8(s16x4 lo, s16x4 hi) { return __builtin_shufflevector(lo, hi, 0, 1, 2, 3, 4, 5, 6, 7); }
; template <int BM, class Epi>
; DI void gemm_tile(const bf16_t* __restrict__ A, int lda, const bf16_t* __restrict__ B, int ldb, int K, int row0, int col0, const Epi& epi, char* smem) {
;     ...
;     for (int kt = 0; kt < nk; ++kt) {
;         const char* cur = smem + (kt & 1) * GSTAGE;
;         char* nxt = smem + ((kt & 1) ^ 1) * GSTAGE;
;         const bool w1 = kt + 1 < nk, l2 = kt + 2 < nk;
;         const bf16_t* a2 = ag + (size_t)(kt + 2) * 64; const bf16_t* b2 = bg + (size_t)(kt + 2) * 64 * ldb;
; #pragma unroll
;         for (int s = 0; s < 4; ++s) {
;             bf16x8 xf[MI], wf[2];
; #pragma unroll
;             for (int mi = 0; mi < MI; ++mi) xf[mi] = *(const bf16x8*)(cur + xoff + mi * 32 * GA_S + s * 32);
; #pragma unroll
;             for (int ni = 0; ni < 2; ++ni) {
;                 const char* wp = cur + woff + s * 16 * GB_S + ni * 64;
;                 wf[ni] = cat8(tr_read(wp), tr_read(wp + 4 * GB_S));
;             }
; #pragma unroll
;             for (int mi = 0; mi < MI; ++mi)
; #pragma unroll
;                 for (int ni = 0; ni < 2; ++ni) acc[mi][ni] = mfma32(wf[ni], xf[mi], acc[mi][ni]);
;             if (w1) {
;                 if (s < NA_) *(u32x4*)(nxt + aw + 64 * s * GA_S) = ra[s];
;                 *(u32x4*)(nxt + bw + 16 * s * GB_S) = rb[s];
;             }
;             if (l2) {
;                 if (s < NA_) ra[s] = *(const u32x4*)(a2 + (size_t)(64 * s) * lda);
;                 rb[s] = *(const u32x4*)(b2 + (size_t)(16 * s) * ldb);
;             }
;         }
	v_mfma_f32_32x32x16_bf16 v[0:15], v[234:237], v[230:233], v[0:15]
	v_mfma_f32_32x32x16_bf16 v[16:31], v[238:241], v[230:233], v[16:31]
	ds_read_b128 v[230:233], v172 offset:13920
	s_waitcnt lgkmcnt(5)
	v_mfma_f32_32x32x16_bf16 v[112:127], v[242:245], v[218:221], v[112:127]
	v_mfma_f32_32x32x16_bf16 v[96:111], v[246:249], v[218:221], v[96:111]
	s_waitcnt lgkmcnt(4)
	v_mfma_f32_32x32x16_bf16 v[80:95], v[242:245], v[222:225], v[80:95]
	v_mfma_f32_32x32x16_bf16 v[64:79], v[246:249], v[222:225], v[64:79]
	s_waitcnt vmcnt(0)
	ds_write_b128 v151, v[188:191] offset:27648
	ds_write_b128 v152, v[128:131] offset:64512
	s_waitcnt lgkmcnt(3)
	v_mfma_f32_32x32x16_bf16 v[32:47], v[242:245], v[226:229], v[32:47]
	v_mfma_f32_32x32x16_bf16 v[48:63], v[246:249], v[226:229], v[48:63]
	s_waitcnt lgkmcnt(2)
	v_mfma_f32_32x32x16_bf16 v[0:15], v[242:245], v[230:233], v[0:15]
	v_mfma_f32_32x32x16_bf16 v[16:31], v[246:249], v[230:233], v[16:31]
	v_add_co_u32_e32 v128, vcc, s1, v144
	s_mov_b32 s1, 0x65c000
	s_nop 0
	v_addc_co_u32_e32 v129, vcc, 0, v145, vcc
	v_add_co_u32_e32 v130, vcc, s1, v144
	s_mov_b32 s1, 0x688000
	s_nop 0
	v_addc_co_u32_e32 v131, vcc, 0, v145, vcc
	v_add_co_u32_e32 v154, vcc, s1, v144
	s_mov_b32 s1, 0x6b4000
	s_nop 0
	v_addc_co_u32_e32 v155, vcc, 0, v145, vcc
	v_add_co_u32_e32 v166, vcc, s1, v144
	s_mov_b32 s1, 0x6e0000
	s_nop 0
	v_addc_co_u32_e32 v167, vcc, 0, v145, vcc
	global_load_dwordx4 v[132:135], v[128:129], off
	global_load_dwordx4 v[158:161], v[130:131], off
	global_load_dwordx4 v[162:165], v[154:155], off
	s_nop 0
	global_load_dwordx4 v[128:131], v[166:167], off
	s_nop 0
	global_load_dwordx4 v[166:169], v[136:137], off offset:1152
	global_load_dwordx4 v[180:183], v[138:139], off offset:1152
	global_load_dwordx4 v[184:187], v[140:141], off offset:1152
	global_load_dwordx4 v[188:191], v[142:143], off offset:1152
	s_waitcnt lgkmcnt(0)
	s_barrier
	ds_read_b64_tr_b16 v[234:235], v149 offset:36864
	ds_read_b64_tr_b16 v[236:237], v149 offset:39168
	ds_read_b128 v[218:221], v148
	ds_read_b64_tr_b16 v[238:239], v149 offset:36928
	ds_read_b64_tr_b16 v[240:241], v149 offset:39232
	ds_read_b128 v[222:225], v148 offset:4608
	ds_read_b128 v[226:229], v148 offset:9216
	ds_read_b128 v[230:233], v148 offset:13824
	s_waitcnt lgkmcnt(5)
	v_mfma_f32_32x32x16_bf16 v[112:127], v[234:237], v[218:221], v[112:127]
	ds_read_b64_tr_b16 v[242:243], v149 offset:46080
	ds_read_b64_tr_b16 v[244:245], v149 offset:48384
	ds_read_b64_tr_b16 v[246:247], v149 offset:46144
	ds_read_b64_tr_b16 v[248:249], v149 offset:48448
	s_waitcnt lgkmcnt(7)
	v_mfma_f32_32x32x16_bf16 v[96:111], v[238:241], v[218:221], v[96:111]
	ds_read_b128 v[218:221], v148 offset:32
	s_waitcnt lgkmcnt(7)
	v_mfma_f32_32x32x16_bf16 v[80:95], v[234:237], v[222:225], v[80:95]
	v_mfma_f32_32x32x16_bf16 v[64:79], v[238:241], v[222:225], v[64:79]
	ds_read_b128 v[222:225], v148 offset:4640
	s_waitcnt vmcnt(3)
	ds_write_b128 v147, v[166:169]
	ds_write_b128 v146, v[132:135] offset:36864
	s_waitcnt lgkmcnt(9)
	v_mfma_f32_32x32x16_bf16 v[32:47], v[234:237], v[226:229], v[32:47]
	v_mfma_f32_32x32x16_bf16 v[48:63], v[238:241], v[226:229], v[48:63]
	ds_read_b128 v[226:229], v148 offset:9248
	s_waitcnt lgkmcnt(9)
	v_mfma_f32_32x32x16_bf16 v[0:15], v[234:237], v[230:233], v[0:15]
	v_mfma_f32_32x32x16_bf16 v[16:31], v[238:241], v[230:233], v[16:31]
	ds_read_b128 v[230:233], v148 offset:13856
	s_waitcnt lgkmcnt(5)
	v_mfma_f32_32x32x16_bf16 v[112:127], v[242:245], v[218:221], v[112:127]
	ds_read_b64_tr_b16 v[234:235], v149 offset:55296
	ds_read_b64_tr_b16 v[236:237], v149 offset:57600
	ds_read_b64_tr_b16 v[238:239], v149 offset:55360
	ds_read_b64_tr_b16 v[240:241], v149 offset:57664
	v_mfma_f32_32x32x16_bf16 v[96:111], v[246:249], v[218:221], v[96:111]
	ds_read_b128 v[218:221], v148 offset:64
	s_waitcnt lgkmcnt(9)
	v_mfma_f32_32x32x16_bf16 v[80:95], v[242:245], v[222:225], v[80:95]
	v_mfma_f32_32x32x16_bf16 v[64:79], v[246:249], v[222:225], v[64:79]
	ds_read_b128 v[222:225], v148 offset:4672
	s_waitcnt vmcnt(2)
	ds_write_b128 v147, v[180:183] offset:9216
	ds_write_b128 v146, v[158:161] offset:46080
	s_waitcnt lgkmcnt(9)
	v_mfma_f32_32x32x16_bf16 v[32:47], v[242:245], v[226:229], v[32:47]
	v_mfma_f32_32x32x16_bf16 v[48:63], v[246:249], v[226:229], v[48:63]
	ds_read_b128 v[226:229], v148 offset:9280
	s_waitcnt lgkmcnt(9)
	v_mfma_f32_32x32x16_bf16 v[0:15], v[242:245], v[230:233], v[0:15]
	v_mfma_f32_32x32x16_bf16 v[16:31], v[246:249], v[230:233], v[16:31]
	ds_read_b128 v[230:233], v148 offset:13888
	s_waitcnt lgkmcnt(5)
	v_mfma_f32_32x32x16_bf16 v[112:127], v[234:237], v[218:221], v[112:127]
	ds_read_b64_tr_b16 v[242:243], v149 offset:64512
	ds_read_b64_tr_b16 v[244:245], v150 offset:29952
	ds_read_b64_tr_b16 v[246:247], v149 offset:64576
	ds_read_b64_tr_b16 v[248:249], v150 offset:30016
	v_mfma_f32_32x32x16_bf16 v[96:111], v[238:241], v[218:221], v[96:111]
	ds_read_b128 v[218:221], v148 offset:96
	s_waitcnt lgkmcnt(9)
	v_mfma_f32_32x32x16_bf16 v[80:95], v[234:237], v[222:225], v[80:95]
	v_mfma_f32_32x32x16_bf16 v[64:79], v[238:241], v[222:225], v[64:79]
	ds_read_b128 v[222:225], v148 offset:4704
	s_waitcnt vmcnt(1)
	ds_write_b128 v147, v[184:187] offset:18432
	ds_write_b128 v146, v[162:165] offset:55296
	s_waitcnt lgkmcnt(9)
	v_mfma_f32_32x32x16_bf16 v[32:47], v[234:237], v[226:229], v[32:47]
	v_mfma_f32_32x32x16_bf16 v[48:63], v[238:241], v[226:229], v[48:63]
	ds_read_b128 v[226:229], v148 offset:9312
	s_waitcnt lgkmcnt(9)
	v_mfma_f32_32x32x16_bf16 v[0:15], v[234:237], v[230:233], v[0:15]
	v_mfma_f32_32x32x16_bf16 v[16:31], v[238:241], v[230:233], v[16:31]
	ds_read_b128 v[230:233], v148 offset:13920
	s_waitcnt lgkmcnt(5)
; DI f32x16 mfma32(bf16x8 a, bf16x8 b, f32x16 c) { return __builtin_amdgcn_mfma_f32_32x32x16_bf16(a, b, c, 0, 0, 0); }
; DI s16x4 tr_read(const char* p) { bfx4 r = __builtin_amdgcn_ds_read_tr16_b64_v4bf16((LDS_AS bfx4*)p); return __builtin_bit_cast(s16x4, r); }
; DI bf16x8 cat8(s16x4 lo, s16x4 hi) { return __builtin_shufflevector(lo, hi, 0, 1, 2, 3, 4, 5, 6, 7); }
; template <int BM, class Epi>
; DI void gemm_tile(const bf16_t* __restrict__ A, int lda, const bf16_t* __restrict__ B, int ldb, int K, int row0, int col0, const Epi& epi, char* smem) {
;     ...
;     for (int kt = 0; kt < nk; ++kt) {
;         const char* cur = smem + (kt & 1) * GSTAGE;
;         char* nxt = smem + ((kt & 1) ^ 1) * GSTAGE;
;         const bool w1 = kt + 1 < nk, l2 = kt + 2 < nk;
;         const bf16_t* a2 = ag + (size_t)(kt + 2) * 64; const bf16_t* b2 = bg + (size_t)(kt + 2) * 64 * ldb;
; #pragma unroll
;         for (int s = 0; s < 4; ++s) {
;             bf16x8 xf[MI], wf[2];
; #pragma unroll
;             for (int mi = 0; mi < MI; ++mi) xf[mi] = *(const bf16x8*)(cur + xoff + mi * 32 * GA_S + s * 32);
; #pragma unroll
;             for (int ni = 0; ni < 2; ++ni) {
;                 const char* wp = cur + woff + s * 16 * GB_S + ni * 64;
;                 wf[ni] = cat8(tr_read(wp), tr_read(wp + 4 * GB_S));
;             }
; #pragma unroll
;             for (int mi = 0; mi < MI; ++mi)
; #pragma unroll
;                 for (int ni = 0; ni < 2; ++ni) acc[mi][ni] = mfma32(wf[ni], xf[mi], acc[mi][ni]);
;             if (w1) {
;                 if (s < NA_) *(u32x4*)(nxt + aw + 64 * s * GA_S) = ra[s];
;                 *(u32x4*)(nxt + bw + 16 * s * GB_S) = rb[s];
;             }
;             if (l2) {
;                 if (s < NA_) ra[s] = *(const u32x4*)(a2 + (size_t)(64 * s) * lda);
;                 rb[s] = *(const u32x4*)(b2 + (size_t)(16 * s) * ldb);
;             }
;         }
	v_mfma_f32_32x32x16_bf16 v[112:127], v[242:245], v[218:221], v[112:127]
	v_mfma_f32_32x32x16_bf16 v[96:111], v[246:249], v[218:221], v[96:111]
	s_waitcnt lgkmcnt(4)
	v_mfma_f32_32x32x16_bf16 v[80:95], v[242:245], v[222:225], v[80:95]
	v_mfma_f32_32x32x16_bf16 v[64:79], v[246:249], v[222:225], v[64:79]
	s_waitcnt vmcnt(0)
	ds_write_b128 v147, v[188:191] offset:27648
	ds_write_b128 v146, v[128:131] offset:64512
	s_waitcnt lgkmcnt(3)
	v_mfma_f32_32x32x16_bf16 v[32:47], v[242:245], v[226:229], v[32:47]
	v_mfma_f32_32x32x16_bf16 v[48:63], v[246:249], v[226:229], v[48:63]
	s_waitcnt lgkmcnt(2)
	v_mfma_f32_32x32x16_bf16 v[0:15], v[242:245], v[230:233], v[0:15]
	v_mfma_f32_32x32x16_bf16 v[16:31], v[246:249], v[230:233], v[16:31]
	v_add_co_u32_e32 v128, vcc, s1, v144
	s_mov_b32 s1, 0x70c000
	s_nop 0
	v_addc_co_u32_e32 v129, vcc, 0, v145, vcc
	v_add_co_u32_e32 v130, vcc, s1, v144
	s_nop 1
	v_addc_co_u32_e32 v131, vcc, 0, v145, vcc
	v_add_co_u32_e32 v154, vcc, s87, v144
	s_nop 1
	v_addc_co_u32_e32 v155, vcc, 0, v145, vcc
	v_add_co_u32_e32 v166, vcc, s4, v144
	s_nop 1
	v_addc_co_u32_e32 v167, vcc, 0, v145, vcc
	global_load_dwordx4 v[132:135], v[128:129], off
	global_load_dwordx4 v[158:161], v[130:131], off
	global_load_dwordx4 v[162:165], v[154:155], off
	s_nop 0
	global_load_dwordx4 v[128:131], v[166:167], off
	s_nop 0
	global_load_dwordx4 v[166:169], v[136:137], off offset:1280
	global_load_dwordx4 v[180:183], v[138:139], off offset:1280
	global_load_dwordx4 v[184:187], v[140:141], off offset:1280
	global_load_dwordx4 v[188:191], v[142:143], off offset:1280
	s_waitcnt lgkmcnt(0)
	s_barrier
	ds_read_b64_tr_b16 v[234:235], v156 offset:36864
	ds_read_b64_tr_b16 v[236:237], v156 offset:39168
	ds_read_b128 v[218:221], v172
	ds_read_b64_tr_b16 v[238:239], v156 offset:36928
	ds_read_b64_tr_b16 v[240:241], v156 offset:39232
	ds_read_b128 v[222:225], v172 offset:4608
	ds_read_b128 v[226:229], v172 offset:9216
	ds_read_b128 v[230:233], v172 offset:13824
	s_waitcnt lgkmcnt(5)
	v_mfma_f32_32x32x16_bf16 v[112:127], v[234:237], v[218:221], v[112:127]
	ds_read_b64_tr_b16 v[242:243], v156 offset:46080
	ds_read_b64_tr_b16 v[244:245], v156 offset:48384
	ds_read_b64_tr_b16 v[246:247], v156 offset:46144
	ds_read_b64_tr_b16 v[248:249], v156 offset:48448
	s_waitcnt lgkmcnt(7)
	v_mfma_f32_32x32x16_bf16 v[96:111], v[238:241], v[218:221], v[96:111]
	ds_read_b128 v[218:221], v172 offset:32
	s_waitcnt lgkmcnt(7)
	v_mfma_f32_32x32x16_bf16 v[80:95], v[234:237], v[222:225], v[80:95]
	v_mfma_f32_32x32x16_bf16 v[64:79], v[238:241], v[222:225], v[64:79]
	ds_read_b128 v[222:225], v172 offset:4640
	s_waitcnt vmcnt(3)
	ds_write_b128 v151, v[166:169]
	ds_write_b128 v152, v[132:135] offset:36864
	s_waitcnt lgkmcnt(9)
	v_mfma_f32_32x32x16_bf16 v[32:47], v[234:237], v[226:229], v[32:47]
	v_mfma_f32_32x32x16_bf16 v[48:63], v[238:241], v[226:229], v[48:63]
	ds_read_b128 v[226:229], v172 offset:9248
	s_waitcnt lgkmcnt(9)
	v_mfma_f32_32x32x16_bf16 v[0:15], v[234:237], v[230:233], v[0:15]
	v_mfma_f32_32x32x16_bf16 v[16:31], v[238:241], v[230:233], v[16:31]
	ds_read_b128 v[230:233], v172 offset:13856
	s_waitcnt lgkmcnt(5)
	v_mfma_f32_32x32x16_bf16 v[112:127], v[242:245], v[218:221], v[112:127]
	ds_read_b64_tr_b16 v[234:235], v156 offset:55296
	ds_read_b64_tr_b16 v[236:237], v156 offset:57600
	ds_read_b64_tr_b16 v[238:239], v156 offset:55360
	ds_read_b64_tr_b16 v[240:241], v156 offset:57664
	v_mfma_f32_32x32x16_bf16 v[96:111], v[246:249], v[218:221], v[96:111]
	ds_read_b128 v[218:221], v172 offset:64
	s_waitcnt lgkmcnt(9)
	v_mfma_f32_32x32x16_bf16 v[80:95], v[242:245], v[222:225], v[80:95]
	v_mfma_f32_32x32x16_bf16 v[64:79], v[246:249], v[222:225], v[64:79]
	ds_read_b128 v[222:225], v172 offset:4672
	s_waitcnt vmcnt(2)
	ds_write_b128 v151, v[180:183] offset:9216
	ds_write_b128 v152, v[158:161] offset:46080
	s_waitcnt lgkmcnt(9)
	v_mfma_f32_32x32x16_bf16 v[32:47], v[242:245], v[226:229], v[32:47]
	v_mfma_f32_32x32x16_bf16 v[48:63], v[246:249], v[226:229], v[48:63]
	ds_read_b128 v[226:229], v172 offset:9280
	s_waitcnt lgkmcnt(9)
	v_mfma_f32_32x32x16_bf16 v[0:15], v[242:245], v[230:233], v[0:15]
	v_mfma_f32_32x32x16_bf16 v[16:31], v[246:249], v[230:233], v[16:31]
	ds_read_b128 v[230:233], v172 offset:13888
	s_waitcnt lgkmcnt(5)
	v_mfma_f32_32x32x16_bf16 v[112:127], v[234:237], v[218:221], v[112:127]
	ds_read_b64_tr_b16 v[242:243], v156 offset:64512
	ds_read_b64_tr_b16 v[244:245], v157 offset:29952
	ds_read_b64_tr_b16 v[246:247], v156 offset:64576
	ds_read_b64_tr_b16 v[248:249], v157 offset:30016
	v_mfma_f32_32x32x16_bf16 v[96:111], v[238:241], v[218:221], v[96:111]
	ds_read_b128 v[218:221], v172 offset:96
	s_waitcnt lgkmcnt(9)
	v_mfma_f32_32x32x16_bf16 v[80:95], v[234:237], v[222:225], v[80:95]
	v_mfma_f32_32x32x16_bf16 v[64:79], v[238:241], v[222:225], v[64:79]
	ds_read_b128 v[222:225], v172 offset:4704
	s_waitcnt vmcnt(1)
	ds_write_b128 v151, v[184:187] offset:18432
	ds_write_b128 v152, v[162:165] offset:55296
	s_waitcnt lgkmcnt(9)
	v_mfma_f32_32x32x16_bf16 v[32:47], v[234:237], v[226:229], v[32:47]
	v_mfma_f32_32x32x16_bf16 v[48:63], v[238:241], v[226:229], v[48:63]
	ds_read_b128 v[226:229], v172 offset:9312
	s_waitcnt lgkmcnt(9)
	v_mfma_f32_32x32x16_bf16 v[0:15], v[234:237], v[230:233], v[0:15]
	v_mfma_f32_32x32x16_bf16 v[16:31], v[238:241], v[230:233], v[16:31]
	ds_read_b128 v[230:233], v172 offset:13920
	s_waitcnt lgkmcnt(5)
	v_mfma_f32_32x32x16_bf16 v[112:127], v[242:245], v[218:221], v[112:127]
	v_mfma_f32_32x32x16_bf16 v[96:111], v[246:249], v[218:221], v[96:111]
	s_waitcnt lgkmcnt(4)
	v_mfma_f32_32x32x16_bf16 v[80:95], v[242:245], v[222:225], v[80:95]
	v_mfma_f32_32x32x16_bf16 v[64:79], v[246:249], v[222:225], v[64:79]
	s_waitcnt vmcnt(0)
	ds_write_b128 v151, v[188:191] offset:27648
	ds_write_b128 v152, v[128:131] offset:64512
	s_waitcnt lgkmcnt(3)
	v_mfma_f32_32x32x16_bf16 v[32:47], v[242:245], v[226:229], v[32:47]
	v_mfma_f32_32x32x16_bf16 v[48:63], v[246:249], v[226:229], v[48:63]
	s_waitcnt lgkmcnt(2)
	v_mfma_f32_32x32x16_bf16 v[0:15], v[242:245], v[230:233], v[0:15]
	v_mfma_f32_32x32x16_bf16 v[16:31], v[246:249], v[230:233], v[16:31]
	v_add_co_u32_e32 v128, vcc, s5, v144
	s_nop 1
	v_addc_co_u32_e32 v129, vcc, 0, v145, vcc
	v_add_co_u32_e32 v130, vcc, s91, v144
	s_nop 1
	v_addc_co_u32_e32 v131, vcc, 0, v145, vcc
	v_add_co_u32_e32 v154, vcc, s96, v144
	s_nop 1
	v_addc_co_u32_e32 v155, vcc, 0, v145, vcc
	v_add_co_u32_e32 v166, vcc, s36, v144
	s_nop 1
	v_addc_co_u32_e32 v167, vcc, 0, v145, vcc
	global_load_dwordx4 v[132:135], v[128:129], off
	global_load_dwordx4 v[158:161], v[130:131], off
	global_load_dwordx4 v[162:165], v[154:155], off
	s_nop 0
	global_load_dwordx4 v[128:131], v[166:167], off
	s_nop 0
	global_load_dwordx4 v[166:169], v[136:137], off offset:1408
	global_load_dwordx4 v[180:183], v[138:139], off offset:1408
	global_load_dwordx4 v[184:187], v[140:141], off offset:1408
	global_load_dwordx4 v[188:191], v[142:143], off offset:1408
	s_waitcnt lgkmcnt(0)
	s_barrier
; DI f32x16 mfma32(bf16x8 a, bf16x8 b, f32x16 c) { return __builtin_amdgcn_mfma_f32_32x32x16_bf16(a, b, c, 0, 0, 0); }
; DI s16x4 tr_read(const char* p) { bfx4 r = __builtin_amdgcn_ds_read_tr16_b64_v4bf16((LDS_AS bfx4*)p); return __builtin_bit_cast(s16x4, r); }
; DI bf16x8 cat8(s16x4 lo, s16x4 hi) { return __builtin_shufflevector(lo, hi, 0, 1, 2, 3, 4, 5, 6, 7); }
; template <int BM, class Epi>
; DI void gemm_tile(const bf16_t* __restrict__ A, int lda, const bf16_t* __restrict__ B, int ldb, int K, int row0, int col0, const Epi& epi, char* smem) {
;     ...
;     for (int kt = 0; kt < nk; ++kt) {
;         const char* cur = smem + (kt & 1) * GSTAGE;
;         char* nxt = smem + ((kt & 1) ^ 1) * GSTAGE;
;         const bool w1 = kt + 1 < nk, l2 = kt + 2 < nk;
;         const bf16_t* a2 = ag + (size_t)(kt + 2) * 64; const bf16_t* b2 = bg + (size_t)(kt + 2) * 64 * ldb;
; #pragma unroll
;         for (int s = 0; s < 4; ++s) {
;             bf16x8 xf[MI], wf[2];
; #pragma unroll
;             for (int mi = 0; mi < MI; ++mi) xf[mi] = *(const bf16x8*)(cur + xoff + mi * 32 * GA_S + s * 32);
; #pragma unroll
;             for (int ni = 0; ni < 2; ++ni) {
;                 const char* wp = cur + woff + s * 16 * GB_S + ni * 64;
;                 wf[ni] = cat8(tr_read(wp), tr_read(wp + 4 * GB_S));
;             }
; #pragma unroll
;             for (int mi = 0; mi < MI; ++mi)
; #pragma unroll
;                 for (int ni = 0; ni < 2; ++ni) acc[mi][ni] = mfma32(wf[ni], xf[mi], acc[mi][ni]);
;             if (w1) {
;                 if (s < NA_) *(u32x4*)(nxt + aw + 64 * s * GA_S) = ra[s];
;                 *(u32x4*)(nxt + bw + 16 * s * GB_S) = rb[s];
;             }
;             if (l2) {
;                 if (s < NA_) ra[s] = *(const u32x4*)(a2 + (size_t)(64 * s) * lda);
;                 rb[s] = *(const u32x4*)(b2 + (size_t)(16 * s) * ldb);
;             }
;         }
	ds_read_b64_tr_b16 v[234:235], v149 offset:36864
	ds_read_b64_tr_b16 v[236:237], v149 offset:39168
	ds_read_b128 v[218:221], v148
	ds_read_b64_tr_b16 v[238:239], v149 offset:36928
	ds_read_b64_tr_b16 v[240:241], v149 offset:39232
	ds_read_b128 v[222:225], v148 offset:4608
	ds_read_b128 v[226:229], v148 offset:9216
	ds_read_b128 v[230:233], v148 offset:13824
	s_waitcnt lgkmcnt(5)
	v_mfma_f32_32x32x16_bf16 v[112:127], v[234:237], v[218:221], v[112:127]
	ds_read_b64_tr_b16 v[242:243], v149 offset:46080
	ds_read_b64_tr_b16 v[244:245], v149 offset:48384
	ds_read_b64_tr_b16 v[246:247], v149 offset:46144
	ds_read_b64_tr_b16 v[248:249], v149 offset:48448
	s_waitcnt lgkmcnt(7)
	v_mfma_f32_32x32x16_bf16 v[96:111], v[238:241], v[218:221], v[96:111]
	ds_read_b128 v[218:221], v148 offset:32
	s_waitcnt lgkmcnt(7)
	v_mfma_f32_32x32x16_bf16 v[80:95], v[234:237], v[222:225], v[80:95]
	v_mfma_f32_32x32x16_bf16 v[64:79], v[238:241], v[222:225], v[64:79]
	ds_read_b128 v[222:225], v148 offset:4640
	s_waitcnt vmcnt(3)
	ds_write_b128 v147, v[166:169]
	ds_write_b128 v146, v[132:135] offset:36864
	s_waitcnt lgkmcnt(9)
	v_mfma_f32_32x32x16_bf16 v[32:47], v[234:237], v[226:229], v[32:47]
	v_mfma_f32_32x32x16_bf16 v[48:63], v[238:241], v[226:229], v[48:63]
	ds_read_b128 v[226:229], v148 offset:9248
	s_waitcnt lgkmcnt(9)
	v_mfma_f32_32x32x16_bf16 v[0:15], v[234:237], v[230:233], v[0:15]
	v_mfma_f32_32x32x16_bf16 v[16:31], v[238:241], v[230:233], v[16:31]
	ds_read_b128 v[230:233], v148 offset:13856
	s_waitcnt lgkmcnt(5)
	v_mfma_f32_32x32x16_bf16 v[112:127], v[242:245], v[218:221], v[112:127]
	ds_read_b64_tr_b16 v[234:235], v149 offset:55296
	ds_read_b64_tr_b16 v[236:237], v149 offset:57600
	ds_read_b64_tr_b16 v[238:239], v149 offset:55360
	ds_read_b64_tr_b16 v[240:241], v149 offset:57664
	v_mfma_f32_32x32x16_bf16 v[96:111], v[246:249], v[218:221], v[96:111]
	ds_read_b128 v[218:221], v148 offset:64
	s_waitcnt lgkmcnt(9)
	v_mfma_f32_32x32x16_bf16 v[80:95], v[242:245], v[222:225], v[80:95]
	v_mfma_f32_32x32x16_bf16 v[64:79], v[246:249], v[222:225], v[64:79]
	ds_read_b128 v[222:225], v148 offset:4672
	s_waitcnt vmcnt(2)
	ds_write_b128 v147, v[180:183] offset:9216
	ds_write_b128 v146, v[158:161] offset:46080
	s_waitcnt lgkmcnt(9)
	v_mfma_f32_32x32x16_bf16 v[32:47], v[242:245], v[226:229], v[32:47]
	v_mfma_f32_32x32x16_bf16 v[48:63], v[246:249], v[226:229], v[48:63]
	ds_read_b128 v[226:229], v148 offset:9280
	s_waitcnt lgkmcnt(9)
	v_mfma_f32_32x32x16_bf16 v[0:15], v[242:245], v[230:233], v[0:15]
	v_mfma_f32_32x32x16_bf16 v[16:31], v[246:249], v[230:233], v[16:31]
	ds_read_b128 v[230:233], v148 offset:13888
	s_waitcnt lgkmcnt(5)
	v_mfma_f32_32x32x16_bf16 v[112:127], v[234:237], v[218:221], v[112:127]
	ds_read_b64_tr_b16 v[242:243], v149 offset:64512
	ds_read_b64_tr_b16 v[244:245], v150 offset:29952
	ds_read_b64_tr_b16 v[246:247], v149 offset:64576
	ds_read_b64_tr_b16 v[248:249], v150 offset:30016
	v_mfma_f32_32x32x16_bf16 v[96:111], v[238:241], v[218:221], v[96:111]
	ds_read_b128 v[218:221], v148 offset:96
	s_waitcnt lgkmcnt(9)
	v_mfma_f32_32x32x16_bf16 v[80:95], v[234:237], v[222:225], v[80:95]
	v_mfma_f32_32x32x16_bf16 v[64:79], v[238:241], v[222:225], v[64:79]
	ds_read_b128 v[222:225], v148 offset:4704
	s_waitcnt vmcnt(1)
	ds_write_b128 v147, v[184:187] offset:18432
	ds_write_b128 v146, v[162:165] offset:55296
	s_waitcnt lgkmcnt(9)
	v_mfma_f32_32x32x16_bf16 v[32:47], v[234:237], v[226:229], v[32:47]
	v_mfma_f32_32x32x16_bf16 v[48:63], v[238:241], v[226:229], v[48:63]
	ds_read_b128 v[226:229], v148 offset:9312
	s_waitcnt lgkmcnt(9)
	v_mfma_f32_32x32x16_bf16 v[0:15], v[234:237], v[230:233], v[0:15]
	v_mfma_f32_32x32x16_bf16 v[16:31], v[238:241], v[230:233], v[16:31]
	ds_read_b128 v[230:233], v148 offset:13920
	s_waitcnt lgkmcnt(5)
	v_mfma_f32_32x32x16_bf16 v[112:127], v[242:245], v[218:221], v[112:127]
	v_mfma_f32_32x32x16_bf16 v[96:111], v[246:249], v[218:221], v[96:111]
	s_waitcnt lgkmcnt(4)
	v_mfma_f32_32x32x16_bf16 v[80:95], v[242:245], v[222:225], v[80:95]
	v_mfma_f32_32x32x16_bf16 v[64:79], v[246:249], v[222:225], v[64:79]
	s_waitcnt vmcnt(0)
	ds_write_b128 v147, v[188:191] offset:27648
	ds_write_b128 v146, v[128:131] offset:64512
	s_waitcnt lgkmcnt(3)
	v_mfma_f32_32x32x16_bf16 v[32:47], v[242:245], v[226:229], v[32:47]
	v_mfma_f32_32x32x16_bf16 v[48:63], v[246:249], v[226:229], v[48:63]
	s_waitcnt lgkmcnt(2)
	v_mfma_f32_32x32x16_bf16 v[0:15], v[242:245], v[230:233], v[0:15]
	v_mfma_f32_32x32x16_bf16 v[16:31], v[246:249], v[230:233], v[16:31]
	v_add_co_u32_e32 v128, vcc, s97, v144
	s_nop 1
	v_addc_co_u32_e32 v129, vcc, 0, v145, vcc
	v_add_co_u32_e32 v130, vcc, s3, v144
	s_nop 1
	v_addc_co_u32_e32 v131, vcc, 0, v145, vcc
	v_add_co_u32_e32 v154, vcc, s19, v144
	s_nop 1
	v_addc_co_u32_e32 v155, vcc, 0, v145, vcc
	v_add_co_u32_e32 v166, vcc, s22, v144
	s_nop 1
	v_addc_co_u32_e32 v167, vcc, 0, v145, vcc
	global_load_dwordx4 v[132:135], v[128:129], off
	global_load_dwordx4 v[158:161], v[130:131], off
	global_load_dwordx4 v[162:165], v[154:155], off
	s_nop 0
	global_load_dwordx4 v[128:131], v[166:167], off
	s_nop 0
	global_load_dwordx4 v[166:169], v[136:137], off offset:1536
	global_load_dwordx4 v[180:183], v[138:139], off offset:1536
	global_load_dwordx4 v[184:187], v[140:141], off offset:1536
	global_load_dwordx4 v[188:191], v[142:143], off offset:1536
	s_waitcnt lgkmcnt(0)
	s_barrier
; DI f32x16 mfma32(bf16x8 a, bf16x8 b, f32x16 c) { return __builtin_amdgcn_mfma_f32_32x32x16_bf16(a, b, c, 0, 0, 0); }
; DI s16x4 tr_read(const char* p) { bfx4 r = __builtin_amdgcn_ds_read_tr16_b64_v4bf16((LDS_AS bfx4*)p); return __builtin_bit_cast(s16x4, r); }
; DI bf16x8 cat8(s16x4 lo, s16x4 hi) { return __builtin_shufflevector(lo, hi, 0, 1, 2, 3, 4, 5, 6, 7); }
; template <int BM, class Epi>
; DI void gemm_tile(const bf16_t* __restrict__ A, int lda, const bf16_t* __restrict__ B, int ldb, int K, int row0, int col0, const Epi& epi, char* smem) {
;     ...
;     for (int kt = 0; kt < nk; ++kt) {
;         const char* cur = smem + (kt & 1) * GSTAGE;
;         char* nxt = smem + ((kt & 1) ^ 1) * GSTAGE;
;         const bool w1 = kt + 1 < nk, l2 = kt + 2 < nk;
;         const bf16_t* a2 = ag + (size_t)(kt + 2) * 64; const bf16_t* b2 = bg + (size_t)(kt + 2) * 64 * ldb;
; #pragma unroll
;         for (int s = 0; s < 4; ++s) {
;             bf16x8 xf[MI], wf[2];
; #pragma unroll
;             for (int mi = 0; mi < MI; ++mi) xf[mi] = *(const bf16x8*)(cur + xoff + mi * 32 * GA_S + s * 32);
; #pragma unroll
;             for (int ni = 0; ni < 2; ++ni) {
;                 const char* wp = cur + woff + s * 16 * GB_S + ni * 64;
;                 wf[ni] = cat8(tr_read(wp), tr_read(wp + 4 * GB_S));
;             }
; #pragma unroll
;             for (int mi = 0; mi < MI; ++mi)
; #pragma unroll
;                 for (int ni = 0; ni < 2; ++ni) acc[mi][ni] = mfma32(wf[ni], xf[mi], acc[mi][ni]);
;             if (w1) {
;                 if (s < NA_) *(u32x4*)(nxt + aw + 64 * s * GA_S) = ra[s];
;                 *(u32x4*)(nxt + bw + 16 * s * GB_S) = rb[s];
;             }
;             if (l2) {
;                 if (s < NA_) ra[s] = *(const u32x4*)(a2 + (size_t)(64 * s) * lda);
;                 rb[s] = *(const u32x4*)(b2 + (size_t)(16 * s) * ldb);
;             }
;         }
	ds_read_b64_tr_b16 v[234:235], v156 offset:36864
	ds_read_b64_tr_b16 v[236:237], v156 offset:39168
	ds_read_b128 v[218:221], v172
	ds_read_b64_tr_b16 v[238:239], v156 offset:36928
	ds_read_b64_tr_b16 v[240:241], v156 offset:39232
	ds_read_b128 v[222:225], v172 offset:4608
	ds_read_b128 v[226:229], v172 offset:9216
	ds_read_b128 v[230:233], v172 offset:13824
	s_waitcnt lgkmcnt(5)
	v_mfma_f32_32x32x16_bf16 v[112:127], v[234:237], v[218:221], v[112:127]
	ds_read_b64_tr_b16 v[242:243], v156 offset:46080
	ds_read_b64_tr_b16 v[244:245], v156 offset:48384
	ds_read_b64_tr_b16 v[246:247], v156 offset:46144
	ds_read_b64_tr_b16 v[248:249], v156 offset:48448
	s_waitcnt lgkmcnt(7)
	v_mfma_f32_32x32x16_bf16 v[96:111], v[238:241], v[218:221], v[96:111]
	ds_read_b128 v[218:221], v172 offset:32
	s_waitcnt lgkmcnt(7)
	v_mfma_f32_32x32x16_bf16 v[80:95], v[234:237], v[222:225], v[80:95]
	v_mfma_f32_32x32x16_bf16 v[64:79], v[238:241], v[222:225], v[64:79]
	ds_read_b128 v[222:225], v172 offset:4640
	s_waitcnt vmcnt(3)
	ds_write_b128 v151, v[166:169]
	ds_write_b128 v152, v[132:135] offset:36864
	s_waitcnt lgkmcnt(9)
	v_mfma_f32_32x32x16_bf16 v[32:47], v[234:237], v[226:229], v[32:47]
	v_mfma_f32_32x32x16_bf16 v[48:63], v[238:241], v[226:229], v[48:63]
	ds_read_b128 v[226:229], v172 offset:9248
	s_waitcnt lgkmcnt(9)
	v_mfma_f32_32x32x16_bf16 v[0:15], v[234:237], v[230:233], v[0:15]
	v_mfma_f32_32x32x16_bf16 v[16:31], v[238:241], v[230:233], v[16:31]
	ds_read_b128 v[230:233], v172 offset:13856
	s_waitcnt lgkmcnt(5)
	v_mfma_f32_32x32x16_bf16 v[112:127], v[242:245], v[218:221], v[112:127]
	ds_read_b64_tr_b16 v[234:235], v156 offset:55296
	ds_read_b64_tr_b16 v[236:237], v156 offset:57600
	ds_read_b64_tr_b16 v[238:239], v156 offset:55360
	ds_read_b64_tr_b16 v[240:241], v156 offset:57664
	v_mfma_f32_32x32x16_bf16 v[96:111], v[246:249], v[218:221], v[96:111]
	ds_read_b128 v[218:221], v172 offset:64
	s_waitcnt lgkmcnt(9)
	v_mfma_f32_32x32x16_bf16 v[80:95], v[242:245], v[222:225], v[80:95]
	v_mfma_f32_32x32x16_bf16 v[64:79], v[246:249], v[222:225], v[64:79]
	ds_read_b128 v[222:225], v172 offset:4672
	s_waitcnt vmcnt(2)
	ds_write_b128 v151, v[180:183] offset:9216
	ds_write_b128 v152, v[158:161] offset:46080
	s_waitcnt lgkmcnt(9)
	v_mfma_f32_32x32x16_bf16 v[32:47], v[242:245], v[226:229], v[32:47]
	v_mfma_f32_32x32x16_bf16 v[48:63], v[246:249], v[226:229], v[48:63]
	ds_read_b128 v[226:229], v172 offset:9280
	s_waitcnt lgkmcnt(9)
	v_mfma_f32_32x32x16_bf16 v[0:15], v[242:245], v[230:233], v[0:15]
	v_mfma_f32_32x32x16_bf16 v[16:31], v[246:249], v[230:233], v[16:31]
	ds_read_b128 v[230:233], v172 offset:13888
	s_waitcnt lgkmcnt(5)
	v_mfma_f32_32x32x16_bf16 v[112:127], v[234:237], v[218:221], v[112:127]
	ds_read_b64_tr_b16 v[242:243], v156 offset:64512
	ds_read_b64_tr_b16 v[244:245], v157 offset:29952
	ds_read_b64_tr_b16 v[246:247], v156 offset:64576
	ds_read_b64_tr_b16 v[248:249], v157 offset:30016
	v_mfma_f32_32x32x16_bf16 v[96:111], v[238:241], v[218:221], v[96:111]
	ds_read_b128 v[218:221], v172 offset:96
	s_waitcnt lgkmcnt(9)
	v_mfma_f32_32x32x16_bf16 v[80:95], v[234:237], v[222:225], v[80:95]
	v_mfma_f32_32x32x16_bf16 v[64:79], v[238:241], v[222:225], v[64:79]
	ds_read_b128 v[222:225], v172 offset:4704
	s_waitcnt vmcnt(1)
	ds_write_b128 v151, v[184:187] offset:18432
	ds_write_b128 v152, v[162:165] offset:55296
	s_waitcnt lgkmcnt(9)
	v_mfma_f32_32x32x16_bf16 v[32:47], v[234:237], v[226:229], v[32:47]
	v_mfma_f32_32x32x16_bf16 v[48:63], v[238:241], v[226:229], v[48:63]
	ds_read_b128 v[226:229], v172 offset:9312
	s_waitcnt lgkmcnt(9)
	v_mfma_f32_32x32x16_bf16 v[0:15], v[234:237], v[230:233], v[0:15]
	v_mfma_f32_32x32x16_bf16 v[16:31], v[238:241], v[230:233], v[16:31]
	ds_read_b128 v[230:233], v172 offset:13920
	s_waitcnt lgkmcnt(5)
	v_mfma_f32_32x32x16_bf16 v[112:127], v[242:245], v[218:221], v[112:127]
	v_mfma_f32_32x32x16_bf16 v[96:111], v[246:249], v[218:221], v[96:111]
	s_waitcnt lgkmcnt(4)
	v_mfma_f32_32x32x16_bf16 v[80:95], v[242:245], v[222:225], v[80:95]
	v_mfma_f32_32x32x16_bf16 v[64:79], v[246:249], v[222:225], v[64:79]
	s_waitcnt vmcnt(0)
	ds_write_b128 v151, v[188:191] offset:27648
	ds_write_b128 v152, v[128:131] offset:64512
	s_waitcnt lgkmcnt(3)
	v_mfma_f32_32x32x16_bf16 v[32:47], v[242:245], v[226:229], v[32:47]
	v_mfma_f32_32x32x16_bf16 v[48:63], v[246:249], v[226:229], v[48:63]
	s_waitcnt lgkmcnt(2)
	v_mfma_f32_32x32x16_bf16 v[0:15], v[242:245], v[230:233], v[0:15]
	v_mfma_f32_32x32x16_bf16 v[16:31], v[246:249], v[230:233], v[16:31]
	v_add_co_u32_e32 v128, vcc, s82, v144
	s_nop 1
	v_addc_co_u32_e32 v129, vcc, 0, v145, vcc
	v_add_co_u32_e32 v130, vcc, s83, v144
	s_nop 1
	v_addc_co_u32_e32 v131, vcc, 0, v145, vcc
	v_add_co_u32_e32 v154, vcc, s20, v144
	s_nop 1
	v_addc_co_u32_e32 v155, vcc, 0, v145, vcc
	v_add_co_u32_e32 v166, vcc, s23, v144
	s_nop 1
	v_addc_co_u32_e32 v167, vcc, 0, v145, vcc
	global_load_dwordx4 v[132:135], v[128:129], off
	global_load_dwordx4 v[158:161], v[130:131], off
	global_load_dwordx4 v[162:165], v[154:155], off
	s_nop 0
	global_load_dwordx4 v[128:131], v[166:167], off
	s_nop 0
	global_load_dwordx4 v[166:169], v[136:137], off offset:1664
	global_load_dwordx4 v[180:183], v[138:139], off offset:1664
	global_load_dwordx4 v[184:187], v[140:141], off offset:1664
	global_load_dwordx4 v[188:191], v[142:143], off offset:1664
	s_waitcnt lgkmcnt(0)
	s_barrier
; DI f32x16 mfma32(bf16x8 a, bf16x8 b, f32x16 c) { return __builtin_amdgcn_mfma_f32_32x32x16_bf16(a, b, c, 0, 0, 0); }
; DI s16x4 tr_read(const char* p) { bfx4 r = __builtin_amdgcn_ds_read_tr16_b64_v4bf16((LDS_AS bfx4*)p); return __builtin_bit_cast(s16x4, r); }
; DI bf16x8 cat8(s16x4 lo, s16x4 hi) { return __builtin_shufflevector(lo, hi, 0, 1, 2, 3, 4, 5, 6, 7); }
; template <int BM, class Epi>
; DI void gemm_tile(const bf16_t* __restrict__ A, int lda, const bf16_t* __restrict__ B, int ldb, int K, int row0, int col0, const Epi& epi, char* smem) {
;     ...
;     for (int kt = 0; kt < nk; ++kt) {
;         const char* cur = smem + (kt & 1) * GSTAGE;
;         char* nxt = smem + ((kt & 1) ^ 1) * GSTAGE;
;         const bool w1 = kt + 1 < nk, l2 = kt + 2 < nk;
;         const bf16_t* a2 = ag + (size_t)(kt + 2) * 64; const bf16_t* b2 = bg + (size_t)(kt + 2) * 64 * ldb;
; #pragma unroll
;         for (int s = 0; s < 4; ++s) {
;             bf16x8 xf[MI], wf[2];
; #pragma unroll
;             for (int mi = 0; mi < MI; ++mi) xf[mi] = *(const bf16x8*)(cur + xoff + mi * 32 * GA_S + s * 32);
; #pragma unroll
;             for (int ni = 0; ni < 2; ++ni) {
;                 const char* wp = cur + woff + s * 16 * GB_S + ni * 64;
;                 wf[ni] = cat8(tr_read(wp), tr_read(wp + 4 * GB_S));
;             }
; #pragma unroll
;             for (int mi = 0; mi < MI; ++mi)
; #pragma unroll
;                 for (int ni = 0; ni < 2; ++ni) acc[mi][ni] = mfma32(wf[ni], xf[mi], acc[mi][ni]);
;             if (w1) {
;                 if (s < NA_) *(u32x4*)(nxt + aw + 64 * s * GA_S) = ra[s];
;                 *(u32x4*)(nxt + bw + 16 * s * GB_S) = rb[s];
;             }
;             if (l2) {
;                 if (s < NA_) ra[s] = *(const u32x4*)(a2 + (size_t)(64 * s) * lda);
;                 rb[s] = *(const u32x4*)(b2 + (size_t)(16 * s) * ldb);
;             }
;         }
	ds_read_b64_tr_b16 v[234:235], v149 offset:36864
	ds_read_b64_tr_b16 v[236:237], v149 offset:39168
	ds_read_b128 v[218:221], v148
	ds_read_b64_tr_b16 v[238:239], v149 offset:36928
	ds_read_b64_tr_b16 v[240:241], v149 offset:39232
	ds_read_b128 v[222:225], v148 offset:4608
	ds_read_b128 v[226:229], v148 offset:9216
	ds_read_b128 v[230:233], v148 offset:13824
	s_waitcnt lgkmcnt(5)
	v_mfma_f32_32x32x16_bf16 v[112:127], v[234:237], v[218:221], v[112:127]
	ds_read_b64_tr_b16 v[242:243], v149 offset:46080
	ds_read_b64_tr_b16 v[244:245], v149 offset:48384
	ds_read_b64_tr_b16 v[246:247], v149 offset:46144
	ds_read_b64_tr_b16 v[248:249], v149 offset:48448
	s_waitcnt lgkmcnt(7)
	v_mfma_f32_32x32x16_bf16 v[96:111], v[238:241], v[218:221], v[96:111]
	ds_read_b128 v[218:221], v148 offset:32
	s_waitcnt lgkmcnt(7)
	v_mfma_f32_32x32x16_bf16 v[80:95], v[234:237], v[222:225], v[80:95]
	v_mfma_f32_32x32x16_bf16 v[64:79], v[238:241], v[222:225], v[64:79]
	ds_read_b128 v[222:225], v148 offset:4640
	s_waitcnt vmcnt(3)
	ds_write_b128 v147, v[166:169]
	ds_write_b128 v146, v[132:135] offset:36864
	s_waitcnt lgkmcnt(9)
	v_mfma_f32_32x32x16_bf16 v[32:47], v[234:237], v[226:229], v[32:47]
	v_mfma_f32_32x32x16_bf16 v[48:63], v[238:241], v[226:229], v[48:63]
	ds_read_b128 v[226:229], v148 offset:9248
	s_waitcnt lgkmcnt(9)
	v_mfma_f32_32x32x16_bf16 v[0:15], v[234:237], v[230:233], v[0:15]
	v_mfma_f32_32x32x16_bf16 v[16:31], v[238:241], v[230:233], v[16:31]
	ds_read_b128 v[230:233], v148 offset:13856
	s_waitcnt lgkmcnt(5)
	v_mfma_f32_32x32x16_bf16 v[112:127], v[242:245], v[218:221], v[112:127]
	ds_read_b64_tr_b16 v[234:235], v149 offset:55296
	ds_read_b64_tr_b16 v[236:237], v149 offset:57600
	ds_read_b64_tr_b16 v[238:239], v149 offset:55360
	ds_read_b64_tr_b16 v[240:241], v149 offset:57664
	v_mfma_f32_32x32x16_bf16 v[96:111], v[246:249], v[218:221], v[96:111]
	ds_read_b128 v[218:221], v148 offset:64
	s_waitcnt lgkmcnt(9)
	v_mfma_f32_32x32x16_bf16 v[80:95], v[242:245], v[222:225], v[80:95]
	v_mfma_f32_32x32x16_bf16 v[64:79], v[246:249], v[222:225], v[64:79]
	ds_read_b128 v[222:225], v148 offset:4672
	s_waitcnt vmcnt(2)
	ds_write_b128 v147, v[180:183] offset:9216
	ds_write_b128 v146, v[158:161] offset:46080
	s_waitcnt lgkmcnt(9)
	v_mfma_f32_32x32x16_bf16 v[32:47], v[242:245], v[226:229], v[32:47]
	v_mfma_f32_32x32x16_bf16 v[48:63], v[246:249], v[226:229], v[48:63]
	ds_read_b128 v[226:229], v148 offset:9280
	s_waitcnt lgkmcnt(9)
	v_mfma_f32_32x32x16_bf16 v[0:15], v[242:245], v[230:233], v[0:15]
	v_mfma_f32_32x32x16_bf16 v[16:31], v[246:249], v[230:233], v[16:31]
	ds_read_b128 v[230:233], v148 offset:13888
	s_waitcnt lgkmcnt(5)
	v_mfma_f32_32x32x16_bf16 v[112:127], v[234:237], v[218:221], v[112:127]
	ds_read_b64_tr_b16 v[242:243], v149 offset:64512
	ds_read_b64_tr_b16 v[244:245], v150 offset:29952
	ds_read_b64_tr_b16 v[246:247], v149 offset:64576
	ds_read_b64_tr_b16 v[248:249], v150 offset:30016
	v_mfma_f32_32x32x16_bf16 v[96:111], v[238:241], v[218:221], v[96:111]
	ds_read_b128 v[218:221], v148 offset:96
	s_waitcnt lgkmcnt(9)
	v_mfma_f32_32x32x16_bf16 v[80:95], v[234:237], v[222:225], v[80:95]
	v_mfma_f32_32x32x16_bf16 v[64:79], v[238:241], v[222:225], v[64:79]
	ds_read_b128 v[222:225], v148 offset:4704
	s_waitcnt vmcnt(1)
	ds_write_b128 v147, v[184:187] offset:18432
	ds_write_b128 v146, v[162:165] offset:55296
	s_waitcnt lgkmcnt(9)
	v_mfma_f32_32x32x16_bf16 v[32:47], v[234:237], v[226:229], v[32:47]
	v_mfma_f32_32x32x16_bf16 v[48:63], v[238:241], v[226:229], v[48:63]
	ds_read_b128 v[226:229], v148 offset:9312
	s_waitcnt lgkmcnt(9)
	v_mfma_f32_32x32x16_bf16 v[0:15], v[234:237], v[230:233], v[0:15]
	v_mfma_f32_32x32x16_bf16 v[16:31], v[238:241], v[230:233], v[16:31]
	ds_read_b128 v[230:233], v148 offset:13920
	s_waitcnt lgkmcnt(5)
	v_mfma_f32_32x32x16_bf16 v[112:127], v[242:245], v[218:221], v[112:127]
	v_mfma_f32_32x32x16_bf16 v[96:111], v[246:249], v[218:221], v[96:111]
	s_waitcnt lgkmcnt(4)
	v_mfma_f32_32x32x16_bf16 v[80:95], v[242:245], v[222:225], v[80:95]
	v_mfma_f32_32x32x16_bf16 v[64:79], v[246:249], v[222:225], v[64:79]
	s_waitcnt vmcnt(0)
	ds_write_b128 v147, v[188:191] offset:27648
	ds_write_b128 v146, v[128:131] offset:64512
	s_waitcnt lgkmcnt(3)
	v_mfma_f32_32x32x16_bf16 v[32:47], v[242:245], v[226:229], v[32:47]
	v_mfma_f32_32x32x16_bf16 v[48:63], v[246:249], v[226:229], v[48:63]
	s_waitcnt lgkmcnt(2)
	v_mfma_f32_32x32x16_bf16 v[0:15], v[242:245], v[230:233], v[0:15]
	v_mfma_f32_32x32x16_bf16 v[16:31], v[246:249], v[230:233], v[16:31]
	v_add_co_u32_e32 v128, vcc, s24, v144
	s_nop 1
	v_addc_co_u32_e32 v129, vcc, 0, v145, vcc
	v_add_co_u32_e32 v130, vcc, s25, v144
	s_nop 1
	v_addc_co_u32_e32 v131, vcc, 0, v145, vcc
	v_add_co_u32_e32 v132, vcc, s26, v144
	s_nop 1
	v_addc_co_u32_e32 v133, vcc, 0, v145, vcc
	v_add_co_u32_e32 v134, vcc, s28, v144
	s_nop 0
	v_addc_co_u32_e32 v135, vcc, 0, v145, vcc
	global_load_dwordx4 v[158:161], v[128:129], off
	global_load_dwordx4 v[162:165], v[130:131], off
	global_load_dwordx4 v[166:169], v[132:133], off
	s_nop 0
	global_load_dwordx4 v[128:131], v[134:135], off
	global_load_dwordx4 v[180:183], v[136:137], off offset:1792
	global_load_dwordx4 v[184:187], v[138:139], off offset:1792
	global_load_dwordx4 v[188:191], v[140:141], off offset:1792
	s_nop 0
	global_load_dwordx4 v[132:135], v[142:143], off offset:1792
	s_waitcnt lgkmcnt(0)
	s_barrier
; DI f32x16 mfma32(bf16x8 a, bf16x8 b, f32x16 c) { return __builtin_amdgcn_mfma_f32_32x32x16_bf16(a, b, c, 0, 0, 0); }
; DI s16x4 tr_read(const char* p) { bfx4 r = __builtin_amdgcn_ds_read_tr16_b64_v4bf16((LDS_AS bfx4*)p); return __builtin_bit_cast(s16x4, r); }
; DI bf16x8 cat8(s16x4 lo, s16x4 hi) { return __builtin_shufflevector(lo, hi, 0, 1, 2, 3, 4, 5, 6, 7); }
; template <int BM, class Epi>
; DI void gemm_tile(const bf16_t* __restrict__ A, int lda, const bf16_t* __restrict__ B, int ldb, int K, int row0, int col0, const Epi& epi, char* smem) {
;     ...
;     for (int kt = 0; kt < nk; ++kt) {
;         const char* cur = smem + (kt & 1) * GSTAGE;
;         char* nxt = smem + ((kt & 1) ^ 1) * GSTAGE;
;         const bool w1 = kt + 1 < nk, l2 = kt + 2 < nk;
;         const bf16_t* a2 = ag + (size_t)(kt + 2) * 64; const bf16_t* b2 = bg + (size_t)(kt + 2) * 64 * ldb;
; #pragma unroll
;         for (int s = 0; s < 4; ++s) {
;             bf16x8 xf[MI], wf[2];
; #pragma unroll
;             for (int mi = 0; mi < MI; ++mi) xf[mi] = *(const bf16x8*)(cur + xoff + mi * 32 * GA_S + s * 32);
; #pragma unroll
;             for (int ni = 0; ni < 2; ++ni) {
;                 const char* wp = cur + woff + s * 16 * GB_S + ni * 64;
;                 wf[ni] = cat8(tr_read(wp), tr_read(wp + 4 * GB_S));
;             }
; #pragma unroll
;             for (int mi = 0; mi < MI; ++mi)
; #pragma unroll
;                 for (int ni = 0; ni < 2; ++ni) acc[mi][ni] = mfma32(wf[ni], xf[mi], acc[mi][ni]);
;             if (w1) {
;                 if (s < NA_) *(u32x4*)(nxt + aw + 64 * s * GA_S) = ra[s];
;                 *(u32x4*)(nxt + bw + 16 * s * GB_S) = rb[s];
;             }
;             if (l2) {
;                 if (s < NA_) ra[s] = *(const u32x4*)(a2 + (size_t)(64 * s) * lda);
;                 rb[s] = *(const u32x4*)(b2 + (size_t)(16 * s) * ldb);
;             }
;         }
	ds_read_b64_tr_b16 v[234:235], v156 offset:36864
	ds_read_b64_tr_b16 v[236:237], v156 offset:39168
	ds_read_b128 v[218:221], v172
	ds_read_b64_tr_b16 v[238:239], v156 offset:36928
	ds_read_b64_tr_b16 v[240:241], v156 offset:39232
	ds_read_b128 v[222:225], v172 offset:4608
	ds_read_b128 v[226:229], v172 offset:9216
	ds_read_b128 v[230:233], v172 offset:13824
	s_waitcnt lgkmcnt(5)
	v_mfma_f32_32x32x16_bf16 v[112:127], v[234:237], v[218:221], v[112:127]
	ds_read_b64_tr_b16 v[242:243], v156 offset:46080
	ds_read_b64_tr_b16 v[244:245], v156 offset:48384
	ds_read_b64_tr_b16 v[246:247], v156 offset:46144
	ds_read_b64_tr_b16 v[248:249], v156 offset:48448
	s_waitcnt lgkmcnt(7)
	v_mfma_f32_32x32x16_bf16 v[96:111], v[238:241], v[218:221], v[96:111]
	ds_read_b128 v[218:221], v172 offset:32
	s_waitcnt lgkmcnt(7)
	v_mfma_f32_32x32x16_bf16 v[80:95], v[234:237], v[222:225], v[80:95]
	v_mfma_f32_32x32x16_bf16 v[64:79], v[238:241], v[222:225], v[64:79]
	ds_read_b128 v[222:225], v172 offset:4640
	s_waitcnt vmcnt(3)
	ds_write_b128 v151, v[180:183]
	ds_write_b128 v152, v[158:161] offset:36864
	s_waitcnt lgkmcnt(9)
	v_mfma_f32_32x32x16_bf16 v[32:47], v[234:237], v[226:229], v[32:47]
	v_mfma_f32_32x32x16_bf16 v[48:63], v[238:241], v[226:229], v[48:63]
	ds_read_b128 v[226:229], v172 offset:9248
	s_waitcnt lgkmcnt(9)
	v_mfma_f32_32x32x16_bf16 v[0:15], v[234:237], v[230:233], v[0:15]
	v_mfma_f32_32x32x16_bf16 v[16:31], v[238:241], v[230:233], v[16:31]
	ds_read_b128 v[230:233], v172 offset:13856
	s_waitcnt lgkmcnt(5)
	v_mfma_f32_32x32x16_bf16 v[112:127], v[242:245], v[218:221], v[112:127]
	ds_read_b64_tr_b16 v[234:235], v156 offset:55296
	ds_read_b64_tr_b16 v[236:237], v156 offset:57600
	ds_read_b64_tr_b16 v[238:239], v156 offset:55360
	ds_read_b64_tr_b16 v[240:241], v156 offset:57664
	v_mfma_f32_32x32x16_bf16 v[96:111], v[246:249], v[218:221], v[96:111]
	ds_read_b128 v[218:221], v172 offset:64
	s_waitcnt lgkmcnt(9)
	v_mfma_f32_32x32x16_bf16 v[80:95], v[242:245], v[222:225], v[80:95]
	v_mfma_f32_32x32x16_bf16 v[64:79], v[246:249], v[222:225], v[64:79]
	ds_read_b128 v[222:225], v172 offset:4672
	s_waitcnt vmcnt(2)
	ds_write_b128 v151, v[184:187] offset:9216
	ds_write_b128 v152, v[162:165] offset:46080
	s_waitcnt lgkmcnt(9)
	v_mfma_f32_32x32x16_bf16 v[32:47], v[242:245], v[226:229], v[32:47]
	v_mfma_f32_32x32x16_bf16 v[48:63], v[246:249], v[226:229], v[48:63]
	ds_read_b128 v[226:229], v172 offset:9280
	s_waitcnt lgkmcnt(9)
	v_mfma_f32_32x32x16_bf16 v[0:15], v[242:245], v[230:233], v[0:15]
	v_mfma_f32_32x32x16_bf16 v[16:31], v[246:249], v[230:233], v[16:31]
	ds_read_b128 v[230:233], v172 offset:13888
	s_waitcnt lgkmcnt(5)
	v_mfma_f32_32x32x16_bf16 v[112:127], v[234:237], v[218:221], v[112:127]
	ds_read_b64_tr_b16 v[242:243], v156 offset:64512
	ds_read_b64_tr_b16 v[244:245], v157 offset:29952
	ds_read_b64_tr_b16 v[246:247], v156 offset:64576
	ds_read_b64_tr_b16 v[248:249], v157 offset:30016
	v_mfma_f32_32x32x16_bf16 v[96:111], v[238:241], v[218:221], v[96:111]
	ds_read_b128 v[218:221], v172 offset:96
	s_waitcnt lgkmcnt(9)
	v_mfma_f32_32x32x16_bf16 v[80:95], v[234:237], v[222:225], v[80:95]
	v_mfma_f32_32x32x16_bf16 v[64:79], v[238:241], v[222:225], v[64:79]
	ds_read_b128 v[222:225], v172 offset:4704
	s_waitcnt vmcnt(1)
	ds_write_b128 v151, v[188:191] offset:18432
	ds_write_b128 v152, v[166:169] offset:55296
	s_waitcnt lgkmcnt(9)
	v_mfma_f32_32x32x16_bf16 v[32:47], v[234:237], v[226:229], v[32:47]
	v_mfma_f32_32x32x16_bf16 v[48:63], v[238:241], v[226:229], v[48:63]
	ds_read_b128 v[226:229], v172 offset:9312
	s_waitcnt lgkmcnt(9)
	v_mfma_f32_32x32x16_bf16 v[0:15], v[234:237], v[230:233], v[0:15]
	v_mfma_f32_32x32x16_bf16 v[16:31], v[238:241], v[230:233], v[16:31]
	ds_read_b128 v[230:233], v172 offset:13920
	s_waitcnt lgkmcnt(5)
	v_mfma_f32_32x32x16_bf16 v[112:127], v[242:245], v[218:221], v[112:127]
	v_mfma_f32_32x32x16_bf16 v[96:111], v[246:249], v[218:221], v[96:111]
	s_waitcnt lgkmcnt(4)
	v_mfma_f32_32x32x16_bf16 v[80:95], v[242:245], v[222:225], v[80:95]
	v_mfma_f32_32x32x16_bf16 v[64:79], v[246:249], v[222:225], v[64:79]
	s_waitcnt vmcnt(0)
	ds_write_b128 v151, v[132:135] offset:27648
	ds_write_b128 v152, v[128:131] offset:64512
	s_waitcnt lgkmcnt(3)
	v_mfma_f32_32x32x16_bf16 v[32:47], v[242:245], v[226:229], v[32:47]
	v_mfma_f32_32x32x16_bf16 v[48:63], v[246:249], v[226:229], v[48:63]
	s_waitcnt lgkmcnt(2)
	v_mfma_f32_32x32x16_bf16 v[0:15], v[242:245], v[230:233], v[0:15]
	v_mfma_f32_32x32x16_bf16 v[16:31], v[246:249], v[230:233], v[16:31]
	v_add_co_u32_e32 v128, vcc, s29, v144
	s_nop 1
	v_addc_co_u32_e32 v129, vcc, 0, v145, vcc
	v_add_co_u32_e32 v130, vcc, s30, v144
	s_nop 1
	v_addc_co_u32_e32 v131, vcc, 0, v145, vcc
	v_add_co_u32_e32 v132, vcc, s31, v144
	s_nop 1
	v_addc_co_u32_e32 v133, vcc, 0, v145, vcc
	v_add_co_u32_e32 v134, vcc, s34, v144
	s_nop 0
	v_addc_co_u32_e32 v135, vcc, 0, v145, vcc
	global_load_dwordx4 v[152:155], v[136:137], off offset:1920
	global_load_dwordx4 v[158:161], v[128:129], off
	s_nop 0
	global_load_dwordx4 v[136:139], v[138:139], off offset:1920
	s_nop 0
	global_load_dwordx4 v[162:165], v[130:131], off
	global_load_dwordx4 v[166:169], v[140:141], off offset:1920
	s_nop 0
	global_load_dwordx4 v[128:131], v[142:143], off offset:1920
	s_nop 0
	global_load_dwordx4 v[140:143], v[132:133], off
	s_nop 0
	global_load_dwordx4 v[132:135], v[134:135], off
	s_waitcnt lgkmcnt(0)
	s_barrier
; DI f32x16 mfma32(bf16x8 a, bf16x8 b, f32x16 c) { return __builtin_amdgcn_mfma_f32_32x32x16_bf16(a, b, c, 0, 0, 0); }
; DI s16x4 tr_read(const char* p) { bfx4 r = __builtin_amdgcn_ds_read_tr16_b64_v4bf16((LDS_AS bfx4*)p); return __builtin_bit_cast(s16x4, r); }
; DI bf16x8 cat8(s16x4 lo, s16x4 hi) { return __builtin_shufflevector(lo, hi, 0, 1, 2, 3, 4, 5, 6, 7); }
; template <int BM, class Epi>
; DI void gemm_tile(const bf16_t* __restrict__ A, int lda, const bf16_t* __restrict__ B, int ldb, int K, int row0, int col0, const Epi& epi, char* smem) {
;     ...
;     for (int kt = 0; kt < nk; ++kt) {
;         const char* cur = smem + (kt & 1) * GSTAGE;
;         char* nxt = smem + ((kt & 1) ^ 1) * GSTAGE;
;         const bool w1 = kt + 1 < nk, l2 = kt + 2 < nk;
;         const bf16_t* a2 = ag + (size_t)(kt + 2) * 64; const bf16_t* b2 = bg + (size_t)(kt + 2) * 64 * ldb;
; #pragma unroll
;         for (int s = 0; s < 4; ++s) {
;             bf16x8 xf[MI], wf[2];
; #pragma unroll
;             for (int mi = 0; mi < MI; ++mi) xf[mi] = *(const bf16x8*)(cur + xoff + mi * 32 * GA_S + s * 32);
; #pragma unroll
;             for (int ni = 0; ni < 2; ++ni) {
;                 const char* wp = cur + woff + s * 16 * GB_S + ni * 64;
;                 wf[ni] = cat8(tr_read(wp), tr_read(wp + 4 * GB_S));
;             }
; #pragma unroll
;             for (int mi = 0; mi < MI; ++mi)
; #pragma unroll
;                 for (int ni = 0; ni < 2; ++ni) acc[mi][ni] = mfma32(wf[ni], xf[mi], acc[mi][ni]);
;             if (w1) {
;                 if (s < NA_) *(u32x4*)(nxt + aw + 64 * s * GA_S) = ra[s];
;                 *(u32x4*)(nxt + bw + 16 * s * GB_S) = rb[s];
;             }
;             if (l2) {
;                 if (s < NA_) ra[s] = *(const u32x4*)(a2 + (size_t)(64 * s) * lda);
;                 rb[s] = *(const u32x4*)(b2 + (size_t)(16 * s) * ldb);
;             }
;         }
;         __syncthreads();
	ds_read_b64_tr_b16 v[180:181], v149 offset:36864
	ds_read_b64_tr_b16 v[182:183], v149 offset:39168
	ds_read_b64_tr_b16 v[186:187], v149 offset:39232
	ds_read_b64_tr_b16 v[184:185], v149 offset:36928
	ds_read_b128 v[188:191], v148
	ds_read_b128 v[218:221], v148 offset:4608
	s_waitcnt lgkmcnt(1)
	v_mfma_f32_32x32x16_bf16 v[112:127], v[180:183], v[188:191], v[112:127]
	v_mfma_f32_32x32x16_bf16 v[96:111], v[184:187], v[188:191], v[96:111]
	s_waitcnt lgkmcnt(0)
	v_mfma_f32_32x32x16_bf16 v[80:95], v[180:183], v[218:221], v[80:95]
	v_mfma_f32_32x32x16_bf16 v[64:79], v[184:187], v[218:221], v[64:79]
	ds_read_b128 v[188:191], v148 offset:9216
	ds_read_b128 v[218:221], v148 offset:13824
	s_waitcnt vmcnt(7)
	ds_write_b128 v147, v[152:155]
	s_waitcnt vmcnt(6)
	ds_write_b128 v146, v[158:161] offset:36864
	s_waitcnt lgkmcnt(3)
	v_mfma_f32_32x32x16_bf16 v[32:47], v[180:183], v[188:191], v[32:47]
	v_mfma_f32_32x32x16_bf16 v[48:63], v[184:187], v[188:191], v[48:63]
	s_waitcnt lgkmcnt(2)
	v_mfma_f32_32x32x16_bf16 v[0:15], v[180:183], v[218:221], v[0:15]
	v_mfma_f32_32x32x16_bf16 v[16:31], v[184:187], v[218:221], v[16:31]
	ds_read_b64_tr_b16 v[152:153], v149 offset:46080
	ds_read_b64_tr_b16 v[154:155], v149 offset:48384
	ds_read_b64_tr_b16 v[160:161], v149 offset:48448
	ds_read_b64_tr_b16 v[158:159], v149 offset:46144
	ds_read_b128 v[180:183], v148 offset:32
	ds_read_b128 v[184:187], v148 offset:4640
	s_waitcnt lgkmcnt(1)
	v_mfma_f32_32x32x16_bf16 v[112:127], v[152:155], v[180:183], v[112:127]
	v_mfma_f32_32x32x16_bf16 v[96:111], v[158:161], v[180:183], v[96:111]
	s_waitcnt lgkmcnt(0)
	v_mfma_f32_32x32x16_bf16 v[80:95], v[152:155], v[184:187], v[80:95]
	v_mfma_f32_32x32x16_bf16 v[64:79], v[158:161], v[184:187], v[64:79]
	ds_read_b128 v[180:183], v148 offset:9248
	ds_read_b128 v[184:187], v148 offset:13856
	s_waitcnt vmcnt(5)
	ds_write_b128 v147, v[136:139] offset:9216
	s_waitcnt vmcnt(4)
	ds_write_b128 v146, v[162:165] offset:46080
	s_waitcnt lgkmcnt(3)
	v_mfma_f32_32x32x16_bf16 v[32:47], v[152:155], v[180:183], v[32:47]
	v_mfma_f32_32x32x16_bf16 v[48:63], v[158:161], v[180:183], v[48:63]
	s_waitcnt lgkmcnt(2)
	v_mfma_f32_32x32x16_bf16 v[0:15], v[152:155], v[184:187], v[0:15]
	v_mfma_f32_32x32x16_bf16 v[16:31], v[158:161], v[184:187], v[16:31]
	ds_read_b64_tr_b16 v[136:137], v149 offset:55296
	ds_read_b64_tr_b16 v[138:139], v149 offset:57600
	ds_read_b64_tr_b16 v[154:155], v149 offset:57664
	ds_read_b64_tr_b16 v[152:153], v149 offset:55360
	ds_read_b128 v[158:161], v148 offset:64
	ds_read_b128 v[162:165], v148 offset:4672
	s_waitcnt lgkmcnt(1)
	v_mfma_f32_32x32x16_bf16 v[112:127], v[136:139], v[158:161], v[112:127]
	v_mfma_f32_32x32x16_bf16 v[96:111], v[152:155], v[158:161], v[96:111]
	s_waitcnt lgkmcnt(0)
	v_mfma_f32_32x32x16_bf16 v[80:95], v[136:139], v[162:165], v[80:95]
	v_mfma_f32_32x32x16_bf16 v[64:79], v[152:155], v[162:165], v[64:79]
	ds_read_b128 v[158:161], v148 offset:9280
	ds_read_b128 v[162:165], v148 offset:13888
	s_waitcnt vmcnt(3)
	ds_write_b128 v147, v[166:169] offset:18432
	s_waitcnt vmcnt(1)
	ds_write_b128 v146, v[140:143] offset:55296
	s_waitcnt lgkmcnt(3)
	v_mfma_f32_32x32x16_bf16 v[32:47], v[136:139], v[158:161], v[32:47]
	v_mfma_f32_32x32x16_bf16 v[48:63], v[152:155], v[158:161], v[48:63]
	s_waitcnt lgkmcnt(2)
	v_mfma_f32_32x32x16_bf16 v[0:15], v[136:139], v[162:165], v[0:15]
	v_mfma_f32_32x32x16_bf16 v[16:31], v[152:155], v[162:165], v[16:31]
	ds_read_b64_tr_b16 v[136:137], v149 offset:64512
	ds_read_b64_tr_b16 v[138:139], v150 offset:29952
	ds_read_b64_tr_b16 v[142:143], v150 offset:30016
	ds_read_b64_tr_b16 v[140:141], v149 offset:64576
	ds_read_b128 v[150:153], v148 offset:96
	ds_read_b128 v[158:161], v148 offset:4704
	s_waitcnt lgkmcnt(1)
	v_mfma_f32_32x32x16_bf16 v[112:127], v[136:139], v[150:153], v[112:127]
	v_mfma_f32_32x32x16_bf16 v[96:111], v[140:143], v[150:153], v[96:111]
	s_waitcnt lgkmcnt(0)
	v_mfma_f32_32x32x16_bf16 v[80:95], v[136:139], v[158:161], v[80:95]
	v_mfma_f32_32x32x16_bf16 v[64:79], v[140:143], v[158:161], v[64:79]
	ds_read_b128 v[150:153], v148 offset:9312
	ds_read_b128 v[158:161], v148 offset:13920
	ds_write_b128 v147, v[128:131] offset:27648
	s_waitcnt vmcnt(0)
	ds_write_b128 v146, v[132:135] offset:64512
	s_waitcnt lgkmcnt(0)
	s_barrier
; DI unsigned pk2(float a, float b) { f32x2 v = {a, b}; bfx2 r = __builtin_convertvector(v, bfx2); return __builtin_bit_cast(unsigned, r); }
; DI float silu_f(float x) { return x * __builtin_amdgcn_rcpf(1.f + __expf(-x)); }
; DI f32x16 mfma32(bf16x8 a, bf16x8 b, f32x16 c) { return __builtin_amdgcn_mfma_f32_32x32x16_bf16(a, b, c, 0, 0, 0); }
; DI s16x4 tr_read(const char* p) { bfx4 r = __builtin_amdgcn_ds_read_tr16_b64_v4bf16((LDS_AS bfx4*)p); return __builtin_bit_cast(s16x4, r); }
; DI bf16x8 cat8(s16x4 lo, s16x4 hi) { return __builtin_shufflevector(lo, hi, 0, 1, 2, 3, 4, 5, 6, 7); }
; template <int BM, class Epi>
; DI void gemm_tile(const bf16_t* __restrict__ A, int lda, const bf16_t* __restrict__ B, int ldb, int K, int row0, int col0, const Epi& epi, char* smem) {
;     ...
;         for (int s = 0; s < 4; ++s) {
;             bf16x8 xf[MI], wf[2];
; #pragma unroll
;             for (int mi = 0; mi < MI; ++mi) xf[mi] = *(const bf16x8*)(cur + xoff + mi * 32 * GA_S + s * 32);
; #pragma unroll
;             for (int ni = 0; ni < 2; ++ni) {
;                 const char* wp = cur + woff + s * 16 * GB_S + ni * 64;
;                 wf[ni] = cat8(tr_read(wp), tr_read(wp + 4 * GB_S));
;             }
; #pragma unroll
;             for (int mi = 0; mi < MI; ++mi)
; #pragma unroll
;                 for (int ni = 0; ni < 2; ++ni) acc[mi][ni] = mfma32(wf[ni], xf[mi], acc[mi][ni]);
;     DI void operator()(const f32x16& a0, const f32x16& a1, int row, int cbase, int hh) const {
;         bf16_t* dst = hid + (size_t)row * DFF + (cbase >> 1) + 4 * hh;
; #pragma unroll
;         for (int q4 = 0; q4 < 4; ++q4) {
;             float h[4];
; #pragma unroll
;             for (int j = 0; j < 4; ++j) h[j] = silu_f(a0[4 * q4 + j]) * a1[4 * q4 + j];
;             u32x2 w; w.x = pk2(h[0], h[1]); w.y = pk2(h[2], h[3]);
;             *(u32x2*)(dst + 8 * q4) = w;
;         }
	v_mfma_f32_32x32x16_bf16 v[32:47], v[136:139], v[150:153], v[32:47]
	v_mfma_f32_32x32x16_bf16 v[48:63], v[140:143], v[150:153], v[48:63]
	v_mfma_f32_32x32x16_bf16 v[0:15], v[136:139], v[158:161], v[0:15]
	ds_read_b64_tr_b16 v[136:137], v156 offset:36864
	ds_read_b64_tr_b16 v[138:139], v156 offset:39168
	ds_read_b64_tr_b16 v[134:135], v156 offset:39232
	ds_read_b64_tr_b16 v[132:133], v156 offset:36928
	ds_read_b128 v[128:131], v172
	ds_read_b128 v[148:151], v172 offset:32
	s_waitcnt lgkmcnt(1)
	v_mfma_f32_32x32x16_bf16 v[112:127], v[136:139], v[128:131], v[112:127]
	v_mfma_f32_32x32x16_bf16 v[96:111], v[132:135], v[128:131], v[96:111]
	ds_read_b128 v[128:131], v172 offset:4608
	ds_read_b128 v[152:155], v172 offset:4640
	s_waitcnt lgkmcnt(1)
	v_mfma_f32_32x32x16_bf16 v[80:95], v[136:139], v[128:131], v[80:95]
	v_mfma_f32_32x32x16_bf16 v[64:79], v[132:135], v[128:131], v[64:79]
	ds_read_b128 v[128:131], v172 offset:9216
	ds_read_b128 v[164:167], v172 offset:9248
	v_mfma_f32_32x32x16_bf16 v[16:31], v[140:143], v[158:161], v[16:31]
	s_waitcnt lgkmcnt(1)
	v_mfma_f32_32x32x16_bf16 v[32:47], v[136:139], v[128:131], v[32:47]
	v_mfma_f32_32x32x16_bf16 v[48:63], v[132:135], v[128:131], v[48:63]
	ds_read_b128 v[140:143], v172 offset:13824
	ds_read_b128 v[128:131], v172 offset:13856
	s_waitcnt lgkmcnt(1)
	v_mfma_f32_32x32x16_bf16 v[0:15], v[136:139], v[140:143], v[0:15]
	ds_read_b64_tr_b16 v[144:145], v156 offset:46080
	ds_read_b64_tr_b16 v[146:147], v156 offset:48384
	ds_read_b64_tr_b16 v[138:139], v156 offset:48448
	ds_read_b64_tr_b16 v[136:137], v156 offset:46144
	s_waitcnt lgkmcnt(2)
	v_mfma_f32_32x32x16_bf16 v[112:127], v[144:147], v[148:151], v[112:127]
	s_waitcnt lgkmcnt(0)
	v_mfma_f32_32x32x16_bf16 v[96:111], v[136:139], v[148:151], v[96:111]
	v_mfma_f32_32x32x16_bf16 v[80:95], v[144:147], v[152:155], v[80:95]
	v_mfma_f32_32x32x16_bf16 v[64:79], v[136:139], v[152:155], v[64:79]
	ds_read_b64_tr_b16 v[152:153], v156 offset:55296
	ds_read_b64_tr_b16 v[154:155], v156 offset:57600
	ds_read_b64_tr_b16 v[150:151], v156 offset:57664
	ds_read_b64_tr_b16 v[148:149], v156 offset:55360
	ds_read_b128 v[158:161], v172 offset:64
	ds_read_b128 v[180:183], v172 offset:96
	s_waitcnt lgkmcnt(1)
	v_mfma_f32_32x32x16_bf16 v[112:127], v[152:155], v[158:161], v[112:127]
	v_mfma_f32_32x32x16_bf16 v[96:111], v[148:151], v[158:161], v[96:111]
	ds_read_b128 v[158:161], v172 offset:4672
	ds_read_b128 v[168:171], v172 offset:4704
	s_waitcnt lgkmcnt(1)
	v_mfma_f32_32x32x16_bf16 v[80:95], v[152:155], v[158:161], v[80:95]
	v_mfma_f32_32x32x16_bf16 v[64:79], v[148:151], v[158:161], v[64:79]
	ds_read_b64_tr_b16 v[160:161], v156 offset:64512
	ds_read_b64_tr_b16 v[162:163], v157 offset:29952
	ds_read_b64_tr_b16 v[158:159], v157 offset:30016
	ds_read_b64_tr_b16 v[156:157], v156 offset:64576
	s_waitcnt lgkmcnt(2)
	v_mfma_f32_32x32x16_bf16 v[112:127], v[160:163], v[180:183], v[112:127]
	s_waitcnt lgkmcnt(0)
	v_mfma_f32_32x32x16_bf16 v[96:111], v[156:159], v[180:183], v[96:111]
	s_nop 9
	v_mul_f32_e32 v182, 0xbfb8aa3b, v114
	v_mul_f32_e32 v183, 0xbfb8aa3b, v115
	v_mul_f32_e32 v188, 0xbfb8aa3b, v120
	v_mul_f32_e32 v189, 0xbfb8aa3b, v121
	v_mul_f32_e32 v180, 0xbfb8aa3b, v112
	v_mul_f32_e32 v181, 0xbfb8aa3b, v113
	v_exp_f32_e32 v182, v182
	v_exp_f32_e32 v183, v183
	v_mul_f32_e32 v184, 0xbfb8aa3b, v116
	v_mul_f32_e32 v185, 0xbfb8aa3b, v117
	v_mul_f32_e32 v186, 0xbfb8aa3b, v118
	v_mul_f32_e32 v187, 0xbfb8aa3b, v119
	v_exp_f32_e32 v188, v188
	v_exp_f32_e32 v189, v189
	v_mul_f32_e32 v190, 0xbfb8aa3b, v122
	v_mul_f32_e32 v191, 0xbfb8aa3b, v123
	v_mul_f32_e32 v192, 0xbfb8aa3b, v124
	v_mul_f32_e32 v193, 0xbfb8aa3b, v125
	v_mul_f32_e32 v217, 0xbfb8aa3b, v126
	v_mul_f32_e32 v218, 0xbfb8aa3b, v127
	v_exp_f32_e32 v180, v180
	v_exp_f32_e32 v181, v181
	v_exp_f32_e32 v184, v184
	v_exp_f32_e32 v185, v185
	v_exp_f32_e32 v186, v186
	v_exp_f32_e32 v187, v187
	v_exp_f32_e32 v190, v190
	v_exp_f32_e32 v191, v191
	v_exp_f32_e32 v192, v192
	v_exp_f32_e32 v193, v193
	v_exp_f32_e32 v217, v217
	v_exp_f32_e32 v218, v218
	v_mfma_f32_32x32x16_bf16 v[80:95], v[160:163], v[168:171], v[80:95]
	v_add_f32_e32 v182, 1.0, v182
	v_add_f32_e32 v183, 1.0, v183
	v_add_f32_e32 v188, 1.0, v188
	v_add_f32_e32 v189, 1.0, v189
	v_add_f32_e32 v180, 1.0, v180
	v_add_f32_e32 v181, 1.0, v181
	v_rcp_f32_e32 v182, v182
	v_rcp_f32_e32 v183, v183
	v_add_f32_e32 v184, 1.0, v184
	v_add_f32_e32 v185, 1.0, v185
	v_add_f32_e32 v186, 1.0, v186
	v_add_f32_e32 v187, 1.0, v187
	v_rcp_f32_e32 v188, v188
	v_rcp_f32_e32 v189, v189
	v_add_f32_e32 v190, 1.0, v190
	v_add_f32_e32 v191, 1.0, v191
	v_add_f32_e32 v192, 1.0, v192
	v_add_f32_e32 v193, 1.0, v193
	v_add_f32_e32 v217, 1.0, v217
	v_add_f32_e32 v219, 1.0, v218
	v_rcp_f32_e32 v180, v180
	v_rcp_f32_e32 v181, v181
	v_rcp_f32_e32 v184, v184
	v_rcp_f32_e32 v185, v185
	v_rcp_f32_e32 v186, v186
	v_rcp_f32_e32 v187, v187
	v_rcp_f32_e32 v190, v190
	v_rcp_f32_e32 v191, v191
	v_rcp_f32_e32 v192, v192
	v_rcp_f32_e32 v193, v193
	v_rcp_f32_e32 v218, v217
	v_rcp_f32_e32 v219, v219
	v_pk_mul_f32 v[114:115], v[114:115], v[182:183]
	v_pk_mul_f32 v[120:121], v[120:121], v[188:189]
	v_pk_mul_f32 v[112:113], v[112:113], v[180:181]
	v_pk_mul_f32 v[180:181], v[116:117], v[184:185]
	v_pk_mul_f32 v[182:183], v[118:119], v[186:187]
	v_pk_mul_f32 v[122:123], v[122:123], v[190:191]
	v_pk_mul_f32 v[124:125], v[124:125], v[192:193]
	v_pk_mul_f32 v[126:127], v[126:127], v[218:219]
	v_pk_mul_f32 v[118:119], v[98:99], v[114:115]
	v_pk_mul_f32 v[98:99], v[104:105], v[120:121]
	v_mul_f32_e32 v104, 0xbfb8aa3b, v80
	v_mul_f32_e32 v105, 0xbfb8aa3b, v81
	v_pk_mul_f32 v[116:117], v[96:97], v[112:113]
	v_pk_mul_f32 v[112:113], v[100:101], v[180:181]
; DI unsigned pk2(float a, float b) { f32x2 v = {a, b}; bfx2 r = __builtin_convertvector(v, bfx2); return __builtin_bit_cast(unsigned, r); }
; DI float silu_f(float x) { return x * __builtin_amdgcn_rcpf(1.f + __expf(-x)); }
;     DI void operator()(const f32x16& a0, const f32x16& a1, int row, int cbase, int hh) const {
;         bf16_t* dst = hid + (size_t)row * DFF + (cbase >> 1) + 4 * hh;
; #pragma unroll
;         for (int q4 = 0; q4 < 4; ++q4) {
;             float h[4];
; #pragma unroll
;             for (int j = 0; j < 4; ++j) h[j] = silu_f(a0[4 * q4 + j]) * a1[4 * q4 + j];
;             u32x2 w; w.x = pk2(h[0], h[1]); w.y = pk2(h[2], h[3]);
;             *(u32x2*)(dst + 8 * q4) = w;
;         }
	v_pk_mul_f32 v[114:115], v[102:103], v[182:183]
	v_pk_mul_f32 v[100:101], v[106:107], v[122:123]
	v_pk_mul_f32 v[96:97], v[108:109], v[124:125]
	v_pk_mul_f32 v[102:103], v[110:111], v[126:127]
	v_exp_f32_e32 v104, v104
	v_exp_f32_e32 v105, v105
	v_mul_f32_e32 v106, 0xbfb8aa3b, v82
	v_mul_f32_e32 v107, 0xbfb8aa3b, v83
	v_mul_f32_e32 v108, 0xbfb8aa3b, v84
	v_mul_f32_e32 v109, 0xbfb8aa3b, v85
	v_mul_f32_e32 v110, 0xbfb8aa3b, v86
	v_mul_f32_e32 v111, 0xbfb8aa3b, v87
	v_mul_f32_e32 v124, 0xbfb8aa3b, v92
	v_mul_f32_e32 v125, 0xbfb8aa3b, v93
	v_mul_f32_e32 v126, 0xbfb8aa3b, v94
	v_mul_f32_e32 v127, 0xbfb8aa3b, v95
	v_exp_f32_e32 v106, v106
	v_exp_f32_e32 v107, v107
	v_exp_f32_e32 v108, v108
	v_exp_f32_e32 v109, v109
	v_exp_f32_e32 v110, v110
	v_exp_f32_e32 v111, v111
	v_exp_f32_e32 v124, v124
	v_exp_f32_e32 v125, v125
	v_exp_f32_e32 v126, v126
	v_exp_f32_e32 v127, v127
	v_mfma_f32_32x32x16_bf16 v[64:79], v[156:159], v[168:171], v[64:79]
	v_add_f32_e32 v104, 1.0, v104
	v_add_f32_e32 v105, 1.0, v105
	v_rcp_f32_e32 v104, v104
	v_rcp_f32_e32 v105, v105
	v_add_f32_e32 v106, 1.0, v106
	v_add_f32_e32 v107, 1.0, v107
	v_add_f32_e32 v108, 1.0, v108
	v_add_f32_e32 v109, 1.0, v109
	v_add_f32_e32 v110, 1.0, v110
	v_add_f32_e32 v111, 1.0, v111
	v_add_f32_e32 v124, 1.0, v124
	v_add_f32_e32 v125, 1.0, v125
	v_add_f32_e32 v126, 1.0, v126
	v_add_f32_e32 v127, 1.0, v127
	v_mfma_f32_32x32x16_bf16 v[32:47], v[144:147], v[164:167], v[32:47]
	v_rcp_f32_e32 v106, v106
	v_rcp_f32_e32 v107, v107
	v_rcp_f32_e32 v108, v108
	v_rcp_f32_e32 v109, v109
	v_rcp_f32_e32 v110, v110
	v_rcp_f32_e32 v111, v111
	v_rcp_f32_e32 v124, v124
	v_rcp_f32_e32 v125, v125
	v_rcp_f32_e32 v126, v126
	v_rcp_f32_e32 v127, v127
	v_mul_f32_e32 v120, 0xbfb8aa3b, v88
	v_mul_f32_e32 v121, 0xbfb8aa3b, v89
	v_exp_f32_e32 v120, v120
	v_exp_f32_e32 v121, v121
	v_pk_mul_f32 v[80:81], v[80:81], v[104:105]
	v_pk_mul_f32 v[82:83], v[82:83], v[106:107]
	v_pk_mul_f32 v[84:85], v[84:85], v[108:109]
	v_pk_mul_f32 v[86:87], v[86:87], v[110:111]
	v_pk_mul_f32 v[92:93], v[92:93], v[124:125]
	v_pk_mul_f32 v[94:95], v[94:95], v[126:127]
	v_pk_mul_f32 v[104:105], v[64:65], v[80:81]
	v_or_b32_e32 v64, s0, v178
	v_mul_f32_e32 v122, 0xbfb8aa3b, v90
	v_mul_f32_e32 v123, 0xbfb8aa3b, v91
	v_pk_mul_f32 v[106:107], v[66:67], v[82:83]
	v_pk_mul_f32 v[84:85], v[68:69], v[84:85]
	v_pk_mul_f32 v[86:87], v[70:71], v[86:87]
	v_pk_mul_f32 v[92:93], v[76:77], v[92:93]
	v_pk_mul_f32 v[94:95], v[78:79], v[94:95]
	v_cvt_pk_bf16_f32 v108, v116, v117
	v_add_u32_e32 v116, v64, v179
	ds_read_b128 v[76:79], v172 offset:9280
	ds_read_b128 v[80:83], v172 offset:9312
	ds_read_b128 v[68:71], v172 offset:13888
	ds_read_b128 v[64:67], v172 offset:13920
	v_exp_f32_e32 v122, v122
	v_exp_f32_e32 v123, v123
	v_add_f32_e32 v120, 1.0, v120
	v_add_f32_e32 v121, 1.0, v121
	s_waitcnt lgkmcnt(3)
	v_mfma_f32_32x32x16_bf16 v[32:47], v[152:155], v[76:79], v[32:47]
	v_rcp_f32_e32 v120, v120
	v_rcp_f32_e32 v121, v121
	v_add_f32_e32 v122, 1.0, v122
	v_add_f32_e32 v123, 1.0, v123
	v_rcp_f32_e32 v122, v122
	v_rcp_f32_e32 v123, v123
	v_pk_mul_f32 v[88:89], v[88:89], v[120:121]
	v_mfma_f32_32x32x16_bf16 v[48:63], v[136:139], v[164:167], v[48:63]
	v_mul_f32_e64 v88, v72, v88
	v_mul_f32_e64 v89, v73, v89
	v_and_b32_e32 v72, 0xc0, v177
	v_or_b32_e32 v72, s6, v72
	v_readlane_b32 s0, v253, 3
	v_pk_mul_f32 v[90:91], v[90:91], v[122:123]
	v_ashrrev_i32_e32 v72, 1, v72
	v_readlane_b32 s1, v253, 4
	s_waitcnt lgkmcnt(2)
	v_mfma_f32_32x32x16_bf16 v[32:47], v[160:163], v[80:83], v[32:47]
	v_mul_f32_e64 v90, v74, v90
	v_mul_f32_e64 v91, v75, v91
	v_ashrrev_i32_e32 v73, 31, v72
	v_mov_b64_e32 v[74:75], s[0:1]
	v_lshlrev_b64 v[72:73], 1, v[72:73]
	v_mov_b32_e32 v177, v173
	s_waitcnt lgkmcnt(0)
	s_barrier
	v_mfma_f32_32x32x16_bf16 v[48:63], v[148:151], v[76:79], v[48:63]
	v_or_b32_e32 v78, 32, v116
	v_mad_i64_i32 v[78:79], s[0:1], v78, s27, v[74:75]
	v_lshl_add_u64 v[78:79], v[78:79], 0, v[72:73]
	v_cvt_pk_bf16_f32 v76, v104, v105
	v_cvt_pk_bf16_f32 v77, v106, v107
	v_lshl_add_u64 v[78:79], v[78:79], 0, v[176:177]
	global_store_dwordx2 v[78:79], v[76:77], off
	v_cvt_pk_bf16_f32 v76, v84, v85
	v_cvt_pk_bf16_f32 v77, v86, v87
	global_store_dwordx2 v[78:79], v[76:77], off offset:16
	v_cvt_pk_bf16_f32 v76, v88, v89
	v_cvt_pk_bf16_f32 v77, v90, v91
	global_store_dwordx2 v[78:79], v[76:77], off offset:32
	v_cvt_pk_bf16_f32 v76, v92, v93
	v_cvt_pk_bf16_f32 v77, v94, v95
	global_store_dwordx2 v[78:79], v[76:77], off offset:48
	v_mul_f32_e32 v76, 0xbfb8aa3b, v32
	v_mul_f32_e32 v77, 0xbfb8aa3b, v33
	v_mul_f32_e32 v78, 0xbfb8aa3b, v34
	v_mul_f32_e32 v79, 0xbfb8aa3b, v35
	v_exp_f32_e32 v76, v76
	v_exp_f32_e32 v77, v77
	v_exp_f32_e32 v78, v78
	v_exp_f32_e32 v79, v79
	v_mfma_f32_32x32x16_bf16 v[48:63], v[156:159], v[80:83], v[48:63]
	v_add_f32_e32 v76, 1.0, v76
	v_add_f32_e32 v77, 1.0, v77
	v_add_f32_e32 v78, 1.0, v78
	v_add_f32_e32 v79, 1.0, v79
	v_rcp_f32_e32 v76, v76
	v_rcp_f32_e32 v77, v77
	v_rcp_f32_e32 v78, v78
	v_rcp_f32_e32 v79, v79
	v_mfma_f32_32x32x16_bf16 v[0:15], v[144:147], v[128:131], v[0:15]
	v_mul_f32_e64 v32, v32, v76
	v_mul_f32_e64 v33, v33, v77
	v_mad_i64_i32 v[110:111], s[0:1], v116, s27, v[74:75]
	v_mul_f32_e64 v34, v34, v78
	v_mul_f32_e64 v35, v35, v79
	v_pk_mul_f32 v[32:33], v[48:49], v[32:33]
	v_pk_mul_f32 v[34:35], v[50:51], v[34:35]
	v_cvt_pk_bf16_f32 v32, v32, v33
	v_cvt_pk_bf16_f32 v33, v34, v35
	v_or_b32_e32 v34, 64, v116
	v_mad_i64_i32 v[34:35], s[0:1], v34, s27, v[74:75]
	v_lshl_add_u64 v[34:35], v[34:35], 0, v[72:73]
	v_lshl_add_u64 v[34:35], v[34:35], 0, v[176:177]
	global_store_dwordx2 v[34:35], v[32:33], off
	v_mul_f32_e32 v32, 0xbfb8aa3b, v36
; DI unsigned pk2(float a, float b) { f32x2 v = {a, b}; bfx2 r = __builtin_convertvector(v, bfx2); return __builtin_bit_cast(unsigned, r); }
; DI float silu_f(float x) { return x * __builtin_amdgcn_rcpf(1.f + __expf(-x)); }
;     DI void operator()(const f32x16& a0, const f32x16& a1, int row, int cbase, int hh) const {
;         bf16_t* dst = hid + (size_t)row * DFF + (cbase >> 1) + 4 * hh;
; #pragma unroll
;         for (int q4 = 0; q4 < 4; ++q4) {
;             float h[4];
; #pragma unroll
;             for (int j = 0; j < 4; ++j) h[j] = silu_f(a0[4 * q4 + j]) * a1[4 * q4 + j];
;             u32x2 w; w.x = pk2(h[0], h[1]); w.y = pk2(h[2], h[3]);
;             *(u32x2*)(dst + 8 * q4) = w;
;         }
	v_mul_f32_e32 v33, 0xbfb8aa3b, v37
	v_mul_f32_e32 v48, 0xbfb8aa3b, v38
	v_mul_f32_e32 v49, 0xbfb8aa3b, v39
	v_exp_f32_e32 v32, v32
	v_exp_f32_e32 v33, v33
	v_exp_f32_e32 v48, v48
	v_exp_f32_e32 v49, v49
	v_add_f32_e32 v32, 1.0, v32
	v_add_f32_e32 v33, 1.0, v33
	v_add_f32_e32 v48, 1.0, v48
	v_add_f32_e32 v49, 1.0, v49
	v_rcp_f32_e32 v32, v32
	v_rcp_f32_e32 v33, v33
	v_rcp_f32_e32 v48, v48
	v_rcp_f32_e32 v49, v49
	v_mfma_f32_32x32x16_bf16 v[16:31], v[132:135], v[140:143], v[16:31]
	v_mul_f32_e64 v32, v36, v32
	v_mul_f32_e64 v33, v37, v33
	v_lshl_add_u64 v[110:111], v[110:111], 0, v[72:73]
	v_mul_f32_e64 v36, v38, v48
	v_mul_f32_e64 v37, v39, v49
	v_pk_mul_f32 v[32:33], v[52:53], v[32:33]
	v_pk_mul_f32 v[36:37], v[54:55], v[36:37]
	v_cvt_pk_bf16_f32 v32, v32, v33
	v_cvt_pk_bf16_f32 v33, v36, v37
	global_store_dwordx2 v[34:35], v[32:33], off offset:16
	v_mul_f32_e32 v32, 0xbfb8aa3b, v40
	v_mul_f32_e32 v33, 0xbfb8aa3b, v41
	v_mul_f32_e32 v36, 0xbfb8aa3b, v42
	v_mul_f32_e32 v37, 0xbfb8aa3b, v43
	v_exp_f32_e32 v32, v32
	v_exp_f32_e32 v33, v33
	v_exp_f32_e32 v36, v36
	v_exp_f32_e32 v37, v37
	v_add_f32_e32 v32, 1.0, v32
	v_add_f32_e32 v33, 1.0, v33
	v_add_f32_e32 v36, 1.0, v36
	v_add_f32_e32 v37, 1.0, v37
	v_rcp_f32_e32 v32, v32
	v_rcp_f32_e32 v33, v33
	v_rcp_f32_e32 v36, v36
	v_rcp_f32_e32 v37, v37
	v_mfma_f32_32x32x16_bf16 v[0:15], v[152:155], v[68:71], v[0:15]
	v_mul_f32_e64 v32, v40, v32
	v_mul_f32_e64 v33, v41, v33
	v_cvt_pk_bf16_f32 v109, v118, v119
	v_mul_f32_e64 v36, v42, v36
	v_mul_f32_e64 v37, v43, v37
	v_pk_mul_f32 v[32:33], v[56:57], v[32:33]
	v_pk_mul_f32 v[36:37], v[58:59], v[36:37]
	v_cvt_pk_bf16_f32 v32, v32, v33
	v_cvt_pk_bf16_f32 v33, v36, v37
	v_mul_f32_e32 v36, 0xbfb8aa3b, v44
	v_mul_f32_e32 v37, 0xbfb8aa3b, v45
	v_exp_f32_e32 v36, v36
	v_exp_f32_e32 v37, v37
	global_store_dwordx2 v[34:35], v[32:33], off offset:32
	v_mfma_f32_32x32x16_bf16 v[16:31], v[136:139], v[128:131], v[16:31]
	v_add_f32_e32 v32, 1.0, v36
	v_add_f32_e32 v33, 1.0, v37
	v_mul_f32_e32 v36, 0xbfb8aa3b, v46
	v_mul_f32_e32 v37, 0xbfb8aa3b, v47
	v_exp_f32_e32 v36, v36
	v_exp_f32_e32 v37, v37
	v_rcp_f32_e32 v32, v32
	v_mfma_f32_32x32x16_bf16 v[0:15], v[160:163], v[64:67], v[0:15]
	v_add_f32_e32 v36, 1.0, v36
	v_add_f32_e32 v37, 1.0, v37
	v_rcp_f32_e32 v33, v33
	v_rcp_f32_e32 v36, v36
	v_rcp_f32_e32 v37, v37
	v_lshl_add_u64 v[110:111], v[110:111], 0, v[176:177]
	v_pk_mul_f32 v[32:33], v[44:45], v[32:33]
	v_mfma_f32_32x32x16_bf16 v[16:31], v[148:151], v[68:71], v[16:31]
	v_mul_f32_e64 v36, v46, v36
	v_mul_f32_e64 v37, v47, v37
	v_mul_f32_e64 v32, v60, v32
	v_mul_f32_e64 v33, v61, v33
	v_mul_f32_e64 v36, v62, v36
	v_mul_f32_e64 v37, v63, v37
	v_cvt_pk_bf16_f32 v32, v32, v33
	v_cvt_pk_bf16_f32 v33, v36, v37
	global_store_dwordx2 v[34:35], v[32:33], off offset:48
	v_mul_f32_e32 v34, 0xbfb8aa3b, v0
	v_mul_f32_e32 v35, 0xbfb8aa3b, v1
	v_exp_f32_e32 v34, v34
	v_exp_f32_e32 v35, v35
	v_mfma_f32_32x32x16_bf16 v[16:31], v[156:159], v[64:67], v[16:31]
	v_mul_f32_e32 v36, 0xbfb8aa3b, v2
	v_add_f32_e32 v34, 1.0, v34
	v_add_f32_e32 v35, 1.0, v35
	v_rcp_f32_e32 v34, v34
	v_rcp_f32_e32 v35, v35
	v_mul_f32_e32 v37, 0xbfb8aa3b, v3
	v_exp_f32_e32 v36, v36
	v_exp_f32_e32 v37, v37
	v_pk_mul_f32 v[0:1], v[0:1], v[34:35]
	v_or_b32_e32 v32, 0x60, v116
	v_add_f32_e32 v34, 1.0, v36
	v_add_f32_e32 v35, 1.0, v37
	v_pk_mul_f32 v[0:1], v[16:17], v[0:1]
	v_rcp_f32_e32 v34, v34
	v_rcp_f32_e32 v35, v35
	v_cvt_pk_bf16_f32 v0, v0, v1
	v_mul_f32_e32 v1, 0xbfb8aa3b, v4
	v_exp_f32_e32 v16, v1
	v_mul_f32_e32 v1, 0xbfb8aa3b, v5
	v_exp_f32_e32 v17, v1
	v_pk_mul_f32 v[2:3], v[2:3], v[34:35]
	v_mad_i64_i32 v[32:33], s[0:1], v32, s27, v[74:75]
	v_pk_mul_f32 v[2:3], v[18:19], v[2:3]
	v_lshl_add_u64 v[32:33], v[32:33], 0, v[72:73]
	v_cvt_pk_bf16_f32 v1, v2, v3
	v_add_f32_e32 v2, 1.0, v16
	v_add_f32_e32 v3, 1.0, v17
	v_rcp_f32_e32 v2, v2
	v_mul_f32_e32 v16, 0xbfb8aa3b, v6
	v_mul_f32_e32 v17, 0xbfb8aa3b, v7
	v_rcp_f32_e32 v3, v3
	v_exp_f32_e32 v16, v16
	v_exp_f32_e32 v17, v17
	v_lshl_add_u64 v[32:33], v[32:33], 0, v[176:177]
	global_store_dwordx2 v[32:33], v[0:1], off
	v_pk_mul_f32 v[0:1], v[4:5], v[2:3]
	v_add_f32_e32 v16, 1.0, v16
	v_add_f32_e32 v17, 1.0, v17
	v_pk_mul_f32 v[0:1], v[20:21], v[0:1]
	v_rcp_f32_e32 v16, v16
	v_rcp_f32_e32 v17, v17
	v_cvt_pk_bf16_f32 v0, v0, v1
	v_mul_f32_e32 v1, 0xbfb8aa3b, v8
	v_exp_f32_e32 v4, v1
	v_mul_f32_e32 v1, 0xbfb8aa3b, v9
	v_exp_f32_e32 v5, v1
	v_pk_mul_f32 v[2:3], v[6:7], v[16:17]
	global_store_dwordx2 v[110:111], v[108:109], off
	v_pk_mul_f32 v[2:3], v[22:23], v[2:3]
	v_cvt_pk_bf16_f32 v108, v112, v113
	v_cvt_pk_bf16_f32 v1, v2, v3
	v_add_f32_e32 v2, 1.0, v4
	v_add_f32_e32 v3, 1.0, v5
	v_mul_f32_e32 v4, 0xbfb8aa3b, v10
	v_mul_f32_e32 v5, 0xbfb8aa3b, v11
	v_exp_f32_e32 v4, v4
	v_exp_f32_e32 v5, v5
	v_rcp_f32_e32 v2, v2
	v_rcp_f32_e32 v3, v3
	v_add_f32_e32 v4, 1.0, v4
	v_add_f32_e32 v5, 1.0, v5
	v_rcp_f32_e32 v4, v4
	v_rcp_f32_e32 v5, v5
	global_store_dwordx2 v[32:33], v[0:1], off offset:16
	v_pk_mul_f32 v[0:1], v[8:9], v[2:3]
	v_cvt_pk_bf16_f32 v109, v114, v115
	v_pk_mul_f32 v[0:1], v[24:25], v[0:1]
	v_pk_mul_f32 v[2:3], v[10:11], v[4:5]
	v_cvt_pk_bf16_f32 v0, v0, v1
	v_mul_f32_e32 v1, 0xbfb8aa3b, v12
	v_exp_f32_e32 v4, v1
	v_mul_f32_e32 v1, 0xbfb8aa3b, v13
	v_exp_f32_e32 v5, v1
	v_pk_mul_f32 v[2:3], v[26:27], v[2:3]
	v_cvt_pk_bf16_f32 v98, v98, v99
	v_cvt_pk_bf16_f32 v1, v2, v3
	v_add_f32_e32 v2, 1.0, v4
	v_add_f32_e32 v3, 1.0, v5
	v_mul_f32_e32 v4, 0xbfb8aa3b, v14
	v_mul_f32_e32 v5, 0xbfb8aa3b, v15
	v_exp_f32_e32 v4, v4
	v_exp_f32_e32 v5, v5
	v_rcp_f32_e32 v2, v2
	v_rcp_f32_e32 v3, v3
	v_add_f32_e32 v4, 1.0, v4
	v_add_f32_e32 v5, 1.0, v5
	v_rcp_f32_e32 v4, v4
	v_rcp_f32_e32 v5, v5
	global_store_dwordx2 v[32:33], v[0:1], off offset:32
	v_pk_mul_f32 v[0:1], v[12:13], v[2:3]
	v_cvt_pk_bf16_f32 v99, v100, v101
	v_pk_mul_f32 v[2:3], v[14:15], v[4:5]
	v_pk_mul_f32 v[0:1], v[28:29], v[0:1]
	v_pk_mul_f32 v[2:3], v[30:31], v[2:3]
	v_cvt_pk_bf16_f32 v96, v96, v97
	v_cvt_pk_bf16_f32 v97, v102, v103
	v_cvt_pk_bf16_f32 v0, v0, v1
	v_cvt_pk_bf16_f32 v1, v2, v3
	global_store_dwordx2 v[110:111], v[108:109], off offset:16
	global_store_dwordx2 v[110:111], v[98:99], off offset:32
	global_store_dwordx2 v[110:111], v[96:97], off offset:48
	global_store_dwordx2 v[32:33], v[0:1], off offset:48
	s_cbranch_scc1 .LBB0_1510
